# v31 + branch-A sub-layer-norm row reduction: DPP moves (quad_perm / row_half_mirror / row_mirror) instead of 4 serialized ds_bpermute round trips per row
# baseline (speedup 1.0000x reference)
; __device__ __forceinline__ int crow(int r, int hi) { return (r & 3) + 8 * (r >> 2) + 4 * hi; }
; template <bool NORM>
; __device__ __forceinline__ void out_rows(const f32x16* o, const float* rli_or_null, char* lds, const float* gain, const float gscale,
;                                          const bf16_t* Z, bf16_t* O, const size_t obase  ) {
;   int tid_ = threadIdx.x; asm volatile("" : "+v"(tid_));
;   const int tid = tid_, wid = tid >> 6, lane = tid & 63, r32 = lane & 31, hi = lane >> 5;
;   float* stg = (float*)(lds + wid * STG_WAVE);
;   const int c8 = (lane & 15) * 8, rsub = lane >> 4;
;   u32x4 zq[8];
; #pragma unroll
;   for (int it = 0; it < 8; ++it) zq[it] = __builtin_nontemporal_load((const u32x4*)(Z + obase + (size_t)(it * 4 + rsub) * 1024 + c8));
; #pragma unroll
;   for (int d0 = 0; d0 < 4; ++d0)
; #pragma unroll
;     for (int r = 0; r < 16; ++r) stg[crow(r, hi) * STG_LD + d0 * 32 + r32] = rli_or_null ? o[d0][r] * rli_or_null[r] : o[d0][r];
;   asm volatile("s_waitcnt lgkmcnt(0)" ::: "memory");
;   f32x4 g0 = {1.f, 1.f, 1.f, 1.f}, g1 = {1.f, 1.f, 1.f, 1.f};
;   if constexpr (NORM) { g0 = *(const f32x4*)(gain + c8) * gscale; g1 = *(const f32x4*)(gain + c8 + 4) * gscale; }
; #pragma unroll
;   for (int it = 0; it < 8; ++it) { const int row = it * 4 + rsub;
;     f32x4 v0 = *(const f32x4*)(stg + row * STG_LD + c8), v1 = *(const f32x4*)(stg + row * STG_LD + c8 + 4);
;     const size_t off = obase + (size_t)row * 1024 + c8;
;     const u32x4 zv = zq[it];
;     if constexpr (NORM) {
;       float ssq = (v0[0] * v0[0] + v0[1] * v0[1]) + (v0[2] * v0[2] + v0[3] * v0[3]) + (v1[0] * v1[0] + v1[1] * v1[1]) + (v1[2] * v1[2] + v1[3] * v1[3]);
;       ssq += __shfl_xor(ssq, 1); ssq += __shfl_xor(ssq, 2); ssq += __shfl_xor(ssq, 4); ssq += __shfl_xor(ssq, 8);
.LBB0_212:
	v_mov_b32_e32 v36, v176
	s_waitcnt vmcnt(0)
	s_barrier
	v_ashrrev_i32_e32 v173, 31, v172
	s_movk_i32 s0, 0x4200
	v_lshrrev_b32_e32 v0, 6, v36
	v_mul_lo_u32 v37, v0, s0
	v_lshlrev_b32_e32 v0, 3, v36
	v_lshlrev_b64 v[44:45], 11, v[172:173]
	v_readlane_b32 s0, v249, 34
	v_and_b32_e32 v38, 0x78, v0
	v_lshl_or_b32 v44, s76, 1, v44
	v_readlane_b32 s1, v249, 35
	v_bfe_u32 v40, v36, 4, 2
	v_lshlrev_b32_e32 v0, 1, v38
	v_lshl_add_u64 v[2:3], s[0:1], 0, v[44:45]
	v_lshl_add_u64 v[2:3], v[2:3], 0, v[0:1]
	v_lshlrev_b32_e32 v34, 11, v40
	v_mov_b32_e32 v35, v1
	v_lshl_add_u64 v[2:3], v[2:3], 0, v[34:35]
	s_movk_i32 s0, 0x2000
	v_add_co_u32_e32 v4, vcc, s0, v2
	s_movk_i32 s0, 0x4000
	s_nop 0
	v_addc_co_u32_e32 v5, vcc, 0, v3, vcc
	global_load_dwordx4 v[30:33], v[2:3], off nt
	global_load_dwordx4 v[26:29], v[4:5], off nt
	v_add_co_u32_e32 v4, vcc, s0, v2
	s_movk_i32 s0, 0x6000
	s_nop 0
	v_addc_co_u32_e32 v5, vcc, 0, v3, vcc
	v_add_co_u32_e32 v6, vcc, s0, v2
	s_mov_b32 s0, 0x8000
	s_nop 0
	v_addc_co_u32_e32 v7, vcc, 0, v3, vcc
	global_load_dwordx4 v[22:25], v[4:5], off nt
	global_load_dwordx4 v[18:21], v[6:7], off nt
	v_add_co_u32_e32 v4, vcc, s0, v2
	s_mov_b32 s0, 0xa000
	s_nop 0
	v_addc_co_u32_e32 v5, vcc, 0, v3, vcc
	v_add_co_u32_e32 v6, vcc, s0, v2
	s_mov_b32 s0, 0xc000
	s_nop 0
	v_addc_co_u32_e32 v7, vcc, 0, v3, vcc
	v_and_b32_e32 v39, 31, v36
	v_lshrrev_b32_e32 v36, 3, v36
	global_load_dwordx4 v[14:17], v[4:5], off nt
	global_load_dwordx4 v[10:13], v[6:7], off nt
	v_add_co_u32_e32 v4, vcc, s0, v2
	v_and_b32_e32 v36, 4, v36
	s_nop 0
	v_addc_co_u32_e32 v5, vcc, 0, v3, vcc
	s_mov_b32 s0, 0xe000
	v_add_u32_e32 v41, 0, v37
	v_lshlrev_b32_e32 v37, 2, v39
	v_mul_u32_u24_e32 v36, 0x210, v36
	v_add_co_u32_e32 v2, vcc, s0, v2
	v_add3_u32 v36, v41, v37, v36
	s_nop 0
	v_addc_co_u32_e32 v3, vcc, 0, v3, vcc
	v_add_u32_e32 v37, 0x400, v36
	v_add_u32_e32 v39, 0x1000, v36
	v_add_u32_e32 v42, 0x1400, v36
	v_add_u32_e32 v43, 0x2000, v36
	v_add_u32_e32 v46, 0x2400, v36
	v_add_u32_e32 v48, 0x3200, v36
	global_load_dwordx4 v[6:9], v[4:5], off nt
	s_nop 0
	global_load_dwordx4 v[2:5], v[2:3], off nt
	ds_write2_b32 v36, v80, v96 offset1:32
	ds_write2_b32 v36, v81, v97 offset0:132 offset1:164
	ds_write2_b32 v37, v82, v98 offset0:8 offset1:40
	ds_write2_b32 v37, v83, v99 offset0:140 offset1:172
	ds_write2_b32 v39, v84, v100 offset0:32 offset1:64
	ds_write2_b32 v39, v85, v101 offset0:164 offset1:196
	ds_write2_b32 v42, v86, v102 offset0:40 offset1:72
	ds_write2_b32 v42, v87, v103 offset0:172 offset1:204
	ds_write2_b32 v43, v88, v104 offset0:64 offset1:96
	ds_write2_b32 v43, v89, v105 offset0:196 offset1:228
	ds_write2_b32 v46, v90, v106 offset0:72 offset1:104
	ds_write2_b32 v46, v91, v107 offset0:204 offset1:236
	v_add_u32_e32 v47, 0x3000, v36
	ds_write2_b32 v48, v93, v109 offset0:100 offset1:132
	v_add_u32_e32 v48, 0x3400, v36
	v_add_u32_e32 v49, 0x3600, v36
	ds_write2_b32 v47, v92, v108 offset0:96 offset1:128
	ds_write2_b32 v48, v94, v110 offset0:104 offset1:136
	ds_write2_b32 v49, v95, v111 offset0:108 offset1:140
	ds_write2_b32 v36, v112, v128 offset0:64 offset1:96
	ds_write2_b32 v36, v113, v129 offset0:196 offset1:228
	ds_write2_b32 v37, v114, v130 offset0:72 offset1:104
	ds_write2_b32 v37, v115, v131 offset0:204 offset1:236
	ds_write2_b32 v39, v116, v132 offset0:96 offset1:128
	v_add_u32_e32 v37, 0x1200, v36
	ds_write2_b32 v37, v117, v133 offset0:100 offset1:132
	ds_write2_b32 v42, v118, v134 offset0:104 offset1:136
	v_add_u32_e32 v37, 0x1600, v36
	ds_write2_b32 v37, v119, v135 offset0:108 offset1:140
	ds_write2_b32 v43, v120, v136 offset0:128 offset1:160
	ds_write2_b32 v46, v121, v137 offset0:4 offset1:36
	ds_write2_b32 v46, v122, v138 offset0:136 offset1:168
	v_add_u32_e32 v37, 0x2800, v36
	v_add_u32_e32 v36, 0x3800, v36
	ds_write2_b32 v37, v123, v139 offset0:12 offset1:44
	ds_write2_b32 v47, v124, v140 offset0:160 offset1:192
	ds_write2_b32 v48, v125, v141 offset0:36 offset1:68
	ds_write2_b32 v48, v126, v142 offset0:168 offset1:200
	ds_write2_b32 v36, v127, v143 offset0:44 offset1:76
	s_waitcnt lgkmcnt(0)
	v_lshlrev_b32_e32 v42, 2, v38
	global_load_dwordx4 v[36:39], v42, s[68:69]
	global_load_dwordx4 v[52:55], v42, s[68:69] offset:16
	v_mul_u32_u24_e32 v40, 0x210, v40
	v_add3_u32 v47, v41, v42, v40
	ds_read_b128 v[56:59], v47
	ds_read_b128 v[60:63], v47 offset:16
	v_and_b32_e32 v46, 64, v177
	v_xor_b32_e32 v43, 1, v177
	v_add_u32_e32 v64, 64, v46
	v_cmp_lt_i32_e32 vcc, v43, v64
	s_mov_b32 s0, 0x3f4ccccd
	v_readlane_b32 s44, v248, 50
	v_cndmask_b32_e32 v40, v177, v43, vcc
	v_lshlrev_b32_e32 v46, 2, v40
	s_waitcnt lgkmcnt(1)
	v_pk_mul_f32 v[40:41], v[58:59], v[58:59]
	v_pk_mul_f32 v[42:43], v[56:57], v[56:57]
	v_readlane_b32 s45, v248, 51
	v_pk_mov_b32 v[48:49], v[42:43], v[40:41] op_sel:[1,0]
	v_mov_b32_e32 v43, v41
	v_pk_add_f32 v[40:41], v[48:49], v[42:43]
	s_waitcnt lgkmcnt(0)
	v_pk_mul_f32 v[42:43], v[62:63], v[62:63]
	v_pk_mul_f32 v[48:49], v[60:61], v[60:61]
	v_mov_b32_e32 v50, v42
	v_mov_b32_e32 v51, v48
	v_mov_b32_e32 v48, v43
	v_pk_add_f32 v[42:43], v[50:51], v[48:49]
	v_add_f32_e32 v40, v40, v41
	v_add_f32_e32 v40, v40, v43
	v_add_f32_e32 v40, v42, v40
	s_nop 1
	v_mov_b32_dpp v41, v40 quad_perm:[1,0,3,2] row_mask:0xf bank_mask:0xf
	v_xor_b32_e32 v42, 2, v177
	v_cmp_lt_i32_e32 vcc, v42, v64
	s_waitcnt vmcnt(9)
	v_lshlrev_b32_e32 v51, 16, v30
	v_and_b32_e32 v30, 0xffff0000, v30
	v_cndmask_b32_e32 v42, v177, v42, vcc
	v_lshlrev_b32_e32 v48, 2, v42
	s_waitcnt lgkmcnt(0)
	v_add_f32_e32 v40, v40, v41
	s_nop 1
	v_mov_b32_dpp v41, v40 quad_perm:[2,3,0,1] row_mask:0xf bank_mask:0xf
	v_xor_b32_e32 v42, 4, v177
	v_cmp_lt_i32_e32 vcc, v42, v64
	s_add_i32 s23, s23, s90
	s_waitcnt lgkmcnt(0)
; __device__ __forceinline__ unsigned cvtpk(float lo, float hi) { unsigned r; asm volatile("v_cvt_pk_bf16_f32 %0, %1, %2" : "=v"(r) : "v"(lo), "v"(hi)); return r; }
; __device__ __forceinline__ float silu(float z) { return z * __builtin_amdgcn_rcpf(1.0f + __builtin_amdgcn_exp2f(-1.4426950408889634f * z)); }
; template <bool NORM>
; __device__ __forceinline__ void out_rows(const f32x16* o, const float* rli_or_null, char* lds, const float* gain, const float gscale,
;                                          const bf16_t* Z, bf16_t* O, const size_t obase  ) {
;     ...
;   for (int it = 0; it < 8; ++it) { const int row = it * 4 + rsub;
;     f32x4 v0 = *(const f32x4*)(stg + row * STG_LD + c8), v1 = *(const f32x4*)(stg + row * STG_LD + c8 + 4);
;     const size_t off = obase + (size_t)row * 1024 + c8;
;     const u32x4 zv = zq[it];
;     if constexpr (NORM) {
;       float ssq = (v0[0] * v0[0] + v0[1] * v0[1]) + (v0[2] * v0[2] + v0[3] * v0[3]) + (v1[0] * v1[0] + v1[1] * v1[1]) + (v1[2] * v1[2] + v1[3] * v1[3]);
;       ssq += __shfl_xor(ssq, 1); ssq += __shfl_xor(ssq, 2); ssq += __shfl_xor(ssq, 4); ssq += __shfl_xor(ssq, 8);
;       const float rstd = __builtin_amdgcn_rsqf(ssq * (1.0f / 128.0f) + 1e-6f);
;       v0 = v0 * rstd * g0; v1 = v1 * rstd * g1; }
;     v0[0] *= silu(__uint_as_float(zv.x << 16)); v0[1] *= silu(__uint_as_float(zv.x & 0xffff0000u));
;     v0[2] *= silu(__uint_as_float(zv.y << 16)); v0[3] *= silu(__uint_as_float(zv.y & 0xffff0000u));
;     v1[0] *= silu(__uint_as_float(zv.z << 16)); v1[1] *= silu(__uint_as_float(zv.z & 0xffff0000u));
;     v1[2] *= silu(__uint_as_float(zv.w << 16)); v1[3] *= silu(__uint_as_float(zv.w & 0xffff0000u));
;     u32x4 w = {cvtpk(v0[0], v0[1]), cvtpk(v0[2], v0[3]), cvtpk(v1[0], v1[1]), cvtpk(v1[2], v1[3])};
;     __builtin_nontemporal_store(w, (u32x4*)(O + off)); }
	v_add_f32_e32 v40, v40, v41
	v_cndmask_b32_e32 v42, v177, v42, vcc
	v_lshlrev_b32_e32 v49, 2, v42
	s_nop 1
	v_mov_b32_dpp v41, v40 row_half_mirror row_mask:0xf bank_mask:0xf
	v_xor_b32_e32 v42, 8, v177
	v_cmp_lt_i32_e32 vcc, v42, v64
	s_nop 1
	v_cndmask_b32_e32 v42, v177, v42, vcc
	v_lshlrev_b32_e32 v50, 2, v42
	s_waitcnt lgkmcnt(0)
	v_add_f32_e32 v42, v40, v41
	s_nop 1
	v_mov_b32_dpp v43, v42 row_mirror row_mask:0xf bank_mask:0xf
	s_waitcnt vmcnt(1)
	v_pk_mul_f32 v[40:41], v[36:37], s[0:1] op_sel_hi:[1,0]
	s_waitcnt lgkmcnt(0)
	v_add_f32_e32 v36, v42, v43
	v_fmamk_f32 v36, v36, 0x3c000000, v192
	v_rsq_f32_e32 v64, v36
	s_waitcnt vmcnt(0)
	v_pk_mul_f32 v[36:37], v[52:53], s[0:1] op_sel_hi:[1,0]
	v_pk_mul_f32 v[42:43], v[38:39], s[0:1] op_sel_hi:[1,0]
	v_pk_mul_f32 v[38:39], v[54:55], s[0:1] op_sel_hi:[1,0]
	v_pk_mul_f32 v[52:53], v[56:57], v[64:65] op_sel_hi:[1,0]
	v_pk_mul_f32 v[56:57], v[60:61], v[64:65] op_sel_hi:[1,0]
	v_mul_f32_e32 v60, 0xbfb8aa3b, v51
	v_exp_f32_e32 v60, v60
	v_mul_f32_e32 v61, 0xbfb8aa3b, v30
	v_exp_f32_e32 v61, v61
	v_pk_mul_f32 v[52:53], v[40:41], v[52:53]
	v_add_f32_e32 v60, 1.0, v60
	v_rcp_f32_e32 v60, v60
	v_add_f32_e32 v61, 1.0, v61
	v_rcp_f32_e32 v61, v61
	v_pk_mul_f32 v[54:55], v[58:59], v[64:65] op_sel_hi:[1,0]
	v_mul_f32_e32 v51, v60, v51
	v_mul_f32_e32 v51, v51, v52
	v_lshlrev_b32_e32 v52, 16, v31
	v_and_b32_e32 v31, 0xffff0000, v31
	v_mul_f32_e32 v30, v61, v30
	v_mul_f32_e32 v60, 0xbfb8aa3b, v52
	v_mul_f32_e32 v61, 0xbfb8aa3b, v31
	v_exp_f32_e32 v60, v60
	v_exp_f32_e32 v61, v61
	v_mul_f32_e32 v30, v30, v53
	v_pk_mul_f32 v[58:59], v[62:63], v[64:65] op_sel_hi:[1,0]
	v_add_f32_e32 v53, 1.0, v60
	v_add_f32_e32 v60, 1.0, v61
	v_lshlrev_b32_e32 v61, 16, v32
	v_rcp_f32_e32 v53, v53
	v_mul_f32_e32 v62, 0xbfb8aa3b, v61
	v_exp_f32_e32 v62, v62
	v_pk_mul_f32 v[54:55], v[42:43], v[54:55]
	v_mul_f32_e32 v52, v53, v52
	v_mul_f32_e32 v53, v52, v54
	v_add_f32_e32 v52, 1.0, v62
	v_and_b32_e32 v32, 0xffff0000, v32
	v_rcp_f32_e32 v60, v60
	v_rcp_f32_e32 v52, v52
	v_mul_f32_e32 v54, 0xbfb8aa3b, v32
	v_exp_f32_e32 v54, v54
	v_pk_mul_f32 v[56:57], v[36:37], v[56:57]
	v_mul_f32_e32 v31, v60, v31
	v_mul_f32_e32 v52, v52, v61
	v_mul_f32_e32 v31, v31, v55
	v_mul_f32_e32 v55, v52, v56
	v_add_f32_e32 v52, 1.0, v54
	v_lshlrev_b32_e32 v54, 16, v33
	v_mul_f32_e32 v56, 0xbfb8aa3b, v54
	v_and_b32_e32 v33, 0xffff0000, v33
	v_rcp_f32_e32 v52, v52
	v_exp_f32_e32 v56, v56
	v_mul_f32_e32 v60, 0xbfb8aa3b, v33
	v_exp_f32_e32 v60, v60
	v_mul_f32_e32 v32, v52, v32
	v_add_f32_e32 v52, 1.0, v56
	v_rcp_f32_e32 v52, v52
	v_add_f32_e32 v56, 1.0, v60
	v_rcp_f32_e32 v56, v56
	v_pk_mul_f32 v[58:59], v[38:39], v[58:59]
	v_mul_f32_e32 v52, v52, v54
	v_mul_f32_e32 v32, v32, v57
	v_mul_f32_e32 v57, v52, v58
	v_mul_f32_e32 v33, v56, v33
	v_mul_f32_e32 v33, v33, v59
	v_cvt_pk_bf16_f32 v52, v51, v30
	v_cvt_pk_bf16_f32 v53, v53, v31
	v_cvt_pk_bf16_f32 v54, v55, v32
	v_cvt_pk_bf16_f32 v55, v57, v33
	ds_read_b128 v[56:59], v47 offset:2112
	ds_read_b128 v[60:63], v47 offset:2128
	v_readlane_b32 s0, v248, 54
	s_add_i32 s21, s21, s0
	v_readlane_b32 s0, v248, 47
	s_waitcnt lgkmcnt(1)
	v_pk_mul_f32 v[30:31], v[58:59], v[58:59]
	v_pk_mul_f32 v[32:33], v[56:57], v[56:57]
	s_add_i32 s20, s20, s0
	v_pk_mov_b32 v[64:65], v[32:33], v[30:31] op_sel:[1,0]
	v_mov_b32_e32 v33, v31
	v_pk_add_f32 v[30:31], v[64:65], v[32:33]
	s_waitcnt lgkmcnt(0)
	v_pk_mul_f32 v[32:33], v[62:63], v[62:63]
	v_pk_mul_f32 v[64:65], v[60:61], v[60:61]
	v_mov_b32_e32 v66, v32
	v_mov_b32_e32 v67, v64
	v_mov_b32_e32 v64, v33
	v_pk_add_f32 v[32:33], v[66:67], v[64:65]
	v_add_f32_e32 v30, v30, v31
	v_add_f32_e32 v30, v30, v33
	v_add_f32_e32 v30, v32, v30
	s_nop 1
	v_mov_b32_dpp v31, v30 quad_perm:[1,0,3,2] row_mask:0xf bank_mask:0xf
	v_readlane_b32 s0, v247, 6
	s_cmp_ge_i32 s23, s0
	v_readlane_b32 s1, v248, 55
	s_waitcnt lgkmcnt(0)
	v_add_f32_e32 v30, v30, v31
	s_nop 1
	v_mov_b32_dpp v31, v30 quad_perm:[2,3,0,1] row_mask:0xf bank_mask:0xf
	s_waitcnt lgkmcnt(0)
	v_add_f32_e32 v30, v30, v31
	s_nop 1
	v_mov_b32_dpp v31, v30 row_half_mirror row_mask:0xf bank_mask:0xf
	s_waitcnt lgkmcnt(0)
	v_add_f32_e32 v32, v30, v31
	v_lshl_add_u64 v[30:31], s[44:45], 0, v[44:45]
	s_nop 1
	v_mov_b32_dpp v33, v32 row_mirror row_mask:0xf bank_mask:0xf
	v_lshl_add_u64 v[30:31], v[30:31], 0, v[0:1]
	v_lshlrev_b32_e32 v0, 16, v26
	v_lshl_add_u64 v[44:45], v[30:31], 0, v[34:35]
	v_mul_f32_e32 v35, 0xbfb8aa3b, v0
	v_and_b32_e32 v26, 0xffff0000, v26
	v_exp_f32_e32 v35, v35
	v_mul_f32_e32 v51, 0xbfb8aa3b, v26
	v_exp_f32_e32 v51, v51
	s_waitcnt lgkmcnt(0)
; __device__ __forceinline__ unsigned cvtpk(float lo, float hi) { unsigned r; asm volatile("v_cvt_pk_bf16_f32 %0, %1, %2" : "=v"(r) : "v"(lo), "v"(hi)); return r; }
; __device__ __forceinline__ float silu(float z) { return z * __builtin_amdgcn_rcpf(1.0f + __builtin_amdgcn_exp2f(-1.4426950408889634f * z)); }
; template <bool NORM>
; __device__ __forceinline__ void out_rows(const f32x16* o, const float* rli_or_null, char* lds, const float* gain, const float gscale,
;                                          const bf16_t* Z, bf16_t* O, const size_t obase  ) {
;     ...
;   for (int it = 0; it < 8; ++it) { const int row = it * 4 + rsub;
;     f32x4 v0 = *(const f32x4*)(stg + row * STG_LD + c8), v1 = *(const f32x4*)(stg + row * STG_LD + c8 + 4);
;     const size_t off = obase + (size_t)row * 1024 + c8;
;     const u32x4 zv = zq[it];
;     if constexpr (NORM) {
;       float ssq = (v0[0] * v0[0] + v0[1] * v0[1]) + (v0[2] * v0[2] + v0[3] * v0[3]) + (v1[0] * v1[0] + v1[1] * v1[1]) + (v1[2] * v1[2] + v1[3] * v1[3]);
;       ssq += __shfl_xor(ssq, 1); ssq += __shfl_xor(ssq, 2); ssq += __shfl_xor(ssq, 4); ssq += __shfl_xor(ssq, 8);
;       const float rstd = __builtin_amdgcn_rsqf(ssq * (1.0f / 128.0f) + 1e-6f);
;       v0 = v0 * rstd * g0; v1 = v1 * rstd * g1; }
;     v0[0] *= silu(__uint_as_float(zv.x << 16)); v0[1] *= silu(__uint_as_float(zv.x & 0xffff0000u));
;     v0[2] *= silu(__uint_as_float(zv.y << 16)); v0[3] *= silu(__uint_as_float(zv.y & 0xffff0000u));
;     v1[0] *= silu(__uint_as_float(zv.z << 16)); v1[1] *= silu(__uint_as_float(zv.z & 0xffff0000u));
;     v1[2] *= silu(__uint_as_float(zv.w << 16)); v1[3] *= silu(__uint_as_float(zv.w & 0xffff0000u));
;     u32x4 w = {cvtpk(v0[0], v0[1]), cvtpk(v0[2], v0[3]), cvtpk(v1[0], v1[1]), cvtpk(v1[2], v1[3])};
;     __builtin_nontemporal_store(w, (u32x4*)(O + off)); }
	v_add_f32_e32 v32, v32, v33
	v_fmamk_f32 v32, v32, 0x3c000000, v192
	v_add_f32_e32 v35, 1.0, v35
	v_rsq_f32_e32 v32, v32
	v_rcp_f32_e32 v35, v35
	v_add_f32_e32 v51, 1.0, v51
	v_rcp_f32_e32 v51, v51
	global_store_dwordx4 v[44:45], v[52:55], off nt
	v_pk_mul_f32 v[44:45], v[56:57], v[32:33] op_sel_hi:[1,0]
	v_mul_f32_e32 v0, v35, v0
	v_lshlrev_b32_e32 v35, 16, v27
	v_and_b32_e32 v27, 0xffff0000, v27
	v_pk_mul_f32 v[44:45], v[40:41], v[44:45]
	v_mul_f32_e32 v26, v51, v26
	v_mul_f32_e32 v51, 0xbfb8aa3b, v27
	v_mul_f32_e32 v0, v0, v44
	v_mul_f32_e32 v44, 0xbfb8aa3b, v35
	v_exp_f32_e32 v51, v51
	v_exp_f32_e32 v44, v44
	v_mul_f32_e32 v26, v26, v45
	v_pk_mul_f32 v[52:53], v[58:59], v[32:33] op_sel_hi:[1,0]
	v_add_f32_e32 v45, 1.0, v51
	v_lshlrev_b32_e32 v51, 16, v28
	v_add_f32_e32 v44, 1.0, v44
	v_mul_f32_e32 v56, 0xbfb8aa3b, v51
	v_rcp_f32_e32 v44, v44
	v_exp_f32_e32 v56, v56
	v_rcp_f32_e32 v45, v45
	v_and_b32_e32 v28, 0xffff0000, v28
	v_mul_f32_e32 v35, v44, v35
	v_add_f32_e32 v44, 1.0, v56
	v_mul_f32_e32 v27, v45, v27
	v_rcp_f32_e32 v44, v44
	v_mul_f32_e32 v45, 0xbfb8aa3b, v28
	v_exp_f32_e32 v45, v45
	v_pk_mul_f32 v[52:53], v[42:43], v[52:53]
	v_mul_f32_e32 v44, v44, v51
	v_lshlrev_b32_e32 v51, 16, v29
	v_and_b32_e32 v29, 0xffff0000, v29
	v_mul_f32_e32 v35, v35, v52
	v_mul_f32_e32 v27, v27, v53
	v_add_f32_e32 v45, 1.0, v45
	v_mul_f32_e32 v52, 0xbfb8aa3b, v51
	v_mul_f32_e32 v53, 0xbfb8aa3b, v29
	v_rcp_f32_e32 v45, v45
	v_exp_f32_e32 v52, v52
	v_exp_f32_e32 v53, v53
	v_pk_mul_f32 v[54:55], v[60:61], v[32:33] op_sel_hi:[1,0]
	v_mul_f32_e32 v28, v45, v28
	v_add_f32_e32 v45, 1.0, v52
	v_add_f32_e32 v52, 1.0, v53
	v_rcp_f32_e32 v52, v52
	v_rcp_f32_e32 v45, v45
	v_pk_mul_f32 v[32:33], v[62:63], v[32:33] op_sel_hi:[1,0]
	v_pk_mul_f32 v[54:55], v[36:37], v[54:55]
	v_pk_mul_f32 v[32:33], v[38:39], v[32:33]
	v_mul_f32_e32 v29, v52, v29
	v_mul_f32_e32 v28, v28, v55
	v_mul_f32_e32 v45, v45, v51
	v_mul_f32_e32 v29, v29, v33
	v_mul_f32_e32 v44, v44, v54
	v_mul_f32_e32 v32, v45, v32
	v_cvt_pk_bf16_f32 v26, v0, v26
	v_cvt_pk_bf16_f32 v27, v35, v27
	v_cvt_pk_bf16_f32 v28, v44, v28
	v_cvt_pk_bf16_f32 v29, v32, v29
	ds_read_b128 v[52:55], v47 offset:4224
	ds_read_b128 v[56:59], v47 offset:4240
	s_waitcnt lgkmcnt(1)
	v_pk_mul_f32 v[32:33], v[54:55], v[54:55]
	v_pk_mul_f32 v[44:45], v[52:53], v[52:53]
	s_nop 0
	v_pk_mov_b32 v[60:61], v[44:45], v[32:33] op_sel:[1,0]
	v_mov_b32_e32 v45, v33
	v_pk_add_f32 v[32:33], v[60:61], v[44:45]
	s_waitcnt lgkmcnt(0)
	v_pk_mul_f32 v[44:45], v[58:59], v[58:59]
	v_pk_mul_f32 v[60:61], v[56:57], v[56:57]
	v_mov_b32_e32 v62, v44
	v_mov_b32_e32 v63, v60
	v_mov_b32_e32 v60, v45
	v_pk_add_f32 v[44:45], v[62:63], v[60:61]
	v_add_f32_e32 v0, v32, v33
	v_add_f32_e32 v0, v0, v45
	v_add_f32_e32 v0, v44, v0
	s_nop 1
	v_mov_b32_dpp v32, v0 quad_perm:[1,0,3,2] row_mask:0xf bank_mask:0xf
	s_waitcnt lgkmcnt(0)
	v_add_f32_e32 v0, v0, v32
	s_nop 1
	v_mov_b32_dpp v32, v0 quad_perm:[2,3,0,1] row_mask:0xf bank_mask:0xf
	s_waitcnt lgkmcnt(0)
	v_add_f32_e32 v0, v0, v32
	s_nop 1
	v_mov_b32_dpp v32, v0 row_half_mirror row_mask:0xf bank_mask:0xf
	s_waitcnt lgkmcnt(0)
	v_add_f32_e32 v0, v0, v32
	s_nop 1
	v_mov_b32_dpp v32, v0 row_mirror row_mask:0xf bank_mask:0xf
	s_waitcnt lgkmcnt(0)
	v_add_f32_e32 v0, v0, v32
	v_fmamk_f32 v0, v0, 0x3c000000, v192
	v_rsq_f32_e32 v32, v0
	v_or_b32_e32 v0, 0x2000, v34
	v_lshl_add_u64 v[44:45], v[30:31], 0, v[0:1]
	v_lshlrev_b32_e32 v0, 16, v22
	v_mul_f32_e32 v35, 0xbfb8aa3b, v0
	v_exp_f32_e32 v35, v35
	v_and_b32_e32 v22, 0xffff0000, v22
	v_mul_f32_e32 v51, 0xbfb8aa3b, v22
	v_exp_f32_e32 v51, v51
	v_add_f32_e32 v35, 1.0, v35
	v_rcp_f32_e32 v35, v35
	global_store_dwordx4 v[44:45], v[26:29], off nt
	v_add_f32_e32 v51, 1.0, v51
	v_rcp_f32_e32 v51, v51
	v_pk_mul_f32 v[26:27], v[52:53], v[32:33] op_sel_hi:[1,0]
	v_mul_f32_e32 v0, v35, v0
	v_pk_mul_f32 v[26:27], v[40:41], v[26:27]
	v_mul_f32_e32 v22, v51, v22
	v_mul_f32_e32 v0, v0, v26
	v_lshlrev_b32_e32 v26, 16, v23
	v_and_b32_e32 v23, 0xffff0000, v23
	v_mul_f32_e32 v35, 0xbfb8aa3b, v26
	v_mul_f32_e32 v51, 0xbfb8aa3b, v23
	v_exp_f32_e32 v35, v35
	v_exp_f32_e32 v51, v51
	v_mul_f32_e32 v22, v22, v27
	v_pk_mul_f32 v[28:29], v[54:55], v[32:33] op_sel_hi:[1,0]
	v_add_f32_e32 v27, 1.0, v35
	v_add_f32_e32 v35, 1.0, v51
	v_lshlrev_b32_e32 v51, 16, v24
	v_mul_f32_e32 v52, 0xbfb8aa3b, v51
	v_rcp_f32_e32 v27, v27
	v_exp_f32_e32 v52, v52
	v_pk_mul_f32 v[28:29], v[42:43], v[28:29]
	v_rcp_f32_e32 v35, v35
	v_mul_f32_e32 v26, v27, v26
	v_add_f32_e32 v27, 1.0, v52
	v_and_b32_e32 v24, 0xffff0000, v24
	v_mul_f32_e32 v26, v26, v28
	v_rcp_f32_e32 v27, v27
	v_mul_f32_e32 v28, 0xbfb8aa3b, v24
	v_exp_f32_e32 v28, v28
	v_pk_mul_f32 v[44:45], v[56:57], v[32:33] op_sel_hi:[1,0]
	v_mul_f32_e32 v23, v35, v23
	v_pk_mul_f32 v[44:45], v[36:37], v[44:45]
	v_mul_f32_e32 v23, v23, v29
	v_mul_f32_e32 v27, v27, v51
	v_lshlrev_b32_e32 v29, 16, v25
	v_and_b32_e32 v25, 0xffff0000, v25
	v_mul_f32_e32 v27, v27, v44
	v_add_f32_e32 v28, 1.0, v28
	v_mul_f32_e32 v35, 0xbfb8aa3b, v29
	v_mul_f32_e32 v44, 0xbfb8aa3b, v25
	v_rcp_f32_e32 v28, v28
	v_exp_f32_e32 v35, v35
	v_exp_f32_e32 v44, v44
	v_pk_mul_f32 v[32:33], v[58:59], v[32:33] op_sel_hi:[1,0]
	v_mul_f32_e32 v24, v28, v24
	v_add_f32_e32 v28, 1.0, v35
	v_add_f32_e32 v35, 1.0, v44
	v_rcp_f32_e32 v28, v28
	v_rcp_f32_e32 v35, v35
	v_pk_mul_f32 v[32:33], v[38:39], v[32:33]
	v_mul_f32_e32 v24, v24, v45
	v_mul_f32_e32 v28, v28, v29
	v_mul_f32_e32 v25, v35, v25
	v_mul_f32_e32 v28, v28, v32
	v_mul_f32_e32 v25, v25, v33
	v_cvt_pk_bf16_f32 v22, v0, v22
	v_cvt_pk_bf16_f32 v23, v26, v23
	v_cvt_pk_bf16_f32 v24, v27, v24
	v_cvt_pk_bf16_f32 v25, v28, v25
	ds_read_b128 v[26:29], v47 offset:6336
	ds_read_b128 v[52:55], v47 offset:6352
	s_waitcnt lgkmcnt(1)
; __device__ __forceinline__ unsigned cvtpk(float lo, float hi) { unsigned r; asm volatile("v_cvt_pk_bf16_f32 %0, %1, %2" : "=v"(r) : "v"(lo), "v"(hi)); return r; }
; __device__ __forceinline__ float silu(float z) { return z * __builtin_amdgcn_rcpf(1.0f + __builtin_amdgcn_exp2f(-1.4426950408889634f * z)); }
; template <bool NORM>
; __device__ __forceinline__ void out_rows(const f32x16* o, const float* rli_or_null, char* lds, const float* gain, const float gscale,
;                                          const bf16_t* Z, bf16_t* O, const size_t obase  ) {
;     ...
;   for (int it = 0; it < 8; ++it) { const int row = it * 4 + rsub;
;     f32x4 v0 = *(const f32x4*)(stg + row * STG_LD + c8), v1 = *(const f32x4*)(stg + row * STG_LD + c8 + 4);
;     const size_t off = obase + (size_t)row * 1024 + c8;
;     const u32x4 zv = zq[it];
;     if constexpr (NORM) {
;       float ssq = (v0[0] * v0[0] + v0[1] * v0[1]) + (v0[2] * v0[2] + v0[3] * v0[3]) + (v1[0] * v1[0] + v1[1] * v1[1]) + (v1[2] * v1[2] + v1[3] * v1[3]);
;       ssq += __shfl_xor(ssq, 1); ssq += __shfl_xor(ssq, 2); ssq += __shfl_xor(ssq, 4); ssq += __shfl_xor(ssq, 8);
;       const float rstd = __builtin_amdgcn_rsqf(ssq * (1.0f / 128.0f) + 1e-6f);
;       v0 = v0 * rstd * g0; v1 = v1 * rstd * g1; }
;     v0[0] *= silu(__uint_as_float(zv.x << 16)); v0[1] *= silu(__uint_as_float(zv.x & 0xffff0000u));
;     v0[2] *= silu(__uint_as_float(zv.y << 16)); v0[3] *= silu(__uint_as_float(zv.y & 0xffff0000u));
;     v1[0] *= silu(__uint_as_float(zv.z << 16)); v1[1] *= silu(__uint_as_float(zv.z & 0xffff0000u));
;     v1[2] *= silu(__uint_as_float(zv.w << 16)); v1[3] *= silu(__uint_as_float(zv.w & 0xffff0000u));
;     u32x4 w = {cvtpk(v0[0], v0[1]), cvtpk(v0[2], v0[3]), cvtpk(v1[0], v1[1]), cvtpk(v1[2], v1[3])};
;     __builtin_nontemporal_store(w, (u32x4*)(O + off)); }
	v_pk_mul_f32 v[32:33], v[28:29], v[28:29]
	v_pk_mul_f32 v[44:45], v[26:27], v[26:27]
	s_nop 0
	v_pk_mov_b32 v[56:57], v[44:45], v[32:33] op_sel:[1,0]
	v_mov_b32_e32 v45, v33
	v_pk_add_f32 v[32:33], v[56:57], v[44:45]
	s_waitcnt lgkmcnt(0)
	v_pk_mul_f32 v[44:45], v[54:55], v[54:55]
	v_pk_mul_f32 v[56:57], v[52:53], v[52:53]
	v_mov_b32_e32 v58, v44
	v_mov_b32_e32 v59, v56
	v_mov_b32_e32 v56, v45
	v_pk_add_f32 v[44:45], v[58:59], v[56:57]
	v_add_f32_e32 v0, v32, v33
	v_add_f32_e32 v0, v0, v45
	v_add_f32_e32 v0, v44, v0
	s_nop 1
	v_mov_b32_dpp v32, v0 quad_perm:[1,0,3,2] row_mask:0xf bank_mask:0xf
	s_waitcnt lgkmcnt(0)
	v_add_f32_e32 v0, v0, v32
	s_nop 1
	v_mov_b32_dpp v32, v0 quad_perm:[2,3,0,1] row_mask:0xf bank_mask:0xf
	s_waitcnt lgkmcnt(0)
	v_add_f32_e32 v0, v0, v32
	s_nop 1
	v_mov_b32_dpp v32, v0 row_half_mirror row_mask:0xf bank_mask:0xf
	s_waitcnt lgkmcnt(0)
	v_add_f32_e32 v0, v0, v32
	s_nop 1
	v_mov_b32_dpp v32, v0 row_mirror row_mask:0xf bank_mask:0xf
	s_waitcnt lgkmcnt(0)
	v_add_f32_e32 v0, v0, v32
	v_fmamk_f32 v0, v0, 0x3c000000, v192
	v_rsq_f32_e32 v32, v0
	v_or_b32_e32 v0, 0x4000, v34
	v_lshl_add_u64 v[44:45], v[30:31], 0, v[0:1]
	v_lshlrev_b32_e32 v0, 16, v18
	global_store_dwordx4 v[44:45], v[22:25], off nt
	v_and_b32_e32 v18, 0xffff0000, v18
	s_nop 0
	v_pk_mul_f32 v[22:23], v[26:27], v[32:33] op_sel_hi:[1,0]
	v_pk_mul_f32 v[24:25], v[28:29], v[32:33] op_sel_hi:[1,0]
	v_pk_mul_f32 v[26:27], v[52:53], v[32:33] op_sel_hi:[1,0]
	v_pk_mul_f32 v[28:29], v[54:55], v[32:33] op_sel_hi:[1,0]
	v_mul_f32_e32 v32, 0xbfb8aa3b, v0
	v_exp_f32_e32 v32, v32
	v_mul_f32_e32 v33, 0xbfb8aa3b, v18
	v_exp_f32_e32 v33, v33
	v_pk_mul_f32 v[22:23], v[40:41], v[22:23]
	v_add_f32_e32 v32, 1.0, v32
	v_rcp_f32_e32 v32, v32
	v_add_f32_e32 v33, 1.0, v33
	v_rcp_f32_e32 v33, v33
	v_pk_mul_f32 v[24:25], v[42:43], v[24:25]
	v_mul_f32_e32 v0, v32, v0
	v_mul_f32_e32 v0, v0, v22
	v_lshlrev_b32_e32 v22, 16, v19
	v_and_b32_e32 v19, 0xffff0000, v19
	v_mul_f32_e32 v18, v33, v18
	v_mul_f32_e32 v32, 0xbfb8aa3b, v22
	v_mul_f32_e32 v33, 0xbfb8aa3b, v19
	v_exp_f32_e32 v32, v32
	v_exp_f32_e32 v33, v33
	v_mul_f32_e32 v18, v18, v23
	v_pk_mul_f32 v[26:27], v[36:37], v[26:27]
	v_add_f32_e32 v23, 1.0, v32
	v_add_f32_e32 v32, 1.0, v33
	v_lshlrev_b32_e32 v33, 16, v20
	v_mul_f32_e32 v35, 0xbfb8aa3b, v33
	v_rcp_f32_e32 v23, v23
	v_exp_f32_e32 v35, v35
	v_rcp_f32_e32 v32, v32
	v_and_b32_e32 v20, 0xffff0000, v20
	v_mul_f32_e32 v22, v23, v22
	v_add_f32_e32 v23, 1.0, v35
	v_mul_f32_e32 v22, v22, v24
	v_rcp_f32_e32 v23, v23
	v_mul_f32_e32 v24, 0xbfb8aa3b, v20
	v_exp_f32_e32 v24, v24
	v_mul_f32_e32 v19, v32, v19
	v_mul_f32_e32 v19, v19, v25
	v_mul_f32_e32 v23, v23, v33
	v_lshlrev_b32_e32 v25, 16, v21
	v_and_b32_e32 v21, 0xffff0000, v21
	v_mul_f32_e32 v23, v23, v26
	v_add_f32_e32 v24, 1.0, v24
	v_mul_f32_e32 v26, 0xbfb8aa3b, v25
	v_mul_f32_e32 v32, 0xbfb8aa3b, v21
	v_rcp_f32_e32 v24, v24
	v_exp_f32_e32 v26, v26
	v_exp_f32_e32 v32, v32
	v_pk_mul_f32 v[28:29], v[38:39], v[28:29]
	v_mul_f32_e32 v20, v24, v20
	v_add_f32_e32 v24, 1.0, v26
	v_add_f32_e32 v26, 1.0, v32
	v_rcp_f32_e32 v24, v24
	v_rcp_f32_e32 v26, v26
	v_mul_f32_e32 v20, v20, v27
	v_cvt_pk_bf16_f32 v18, v0, v18
	v_mul_f32_e32 v24, v24, v25
	v_mul_f32_e32 v21, v26, v21
	v_mul_f32_e32 v24, v24, v28
	v_mul_f32_e32 v21, v21, v29
	v_cvt_pk_bf16_f32 v19, v22, v19
	v_cvt_pk_bf16_f32 v20, v23, v20
	v_cvt_pk_bf16_f32 v21, v24, v21
	ds_read_b128 v[22:25], v47 offset:8448
	ds_read_b128 v[26:29], v47 offset:8464
	s_waitcnt lgkmcnt(1)
	v_pk_mul_f32 v[32:33], v[24:25], v[24:25]
	v_pk_mul_f32 v[44:45], v[22:23], v[22:23]
	s_nop 0
	v_pk_mov_b32 v[52:53], v[44:45], v[32:33] op_sel:[1,0]
	v_mov_b32_e32 v45, v33
	v_pk_add_f32 v[32:33], v[52:53], v[44:45]
	s_waitcnt lgkmcnt(0)
	v_pk_mul_f32 v[44:45], v[28:29], v[28:29]
	v_pk_mul_f32 v[52:53], v[26:27], v[26:27]
	v_mov_b32_e32 v54, v44
	v_mov_b32_e32 v55, v52
	v_mov_b32_e32 v52, v45
	v_pk_add_f32 v[44:45], v[54:55], v[52:53]
	v_add_f32_e32 v0, v32, v33
	v_add_f32_e32 v0, v0, v45
	v_add_f32_e32 v0, v44, v0
	s_nop 1
	v_mov_b32_dpp v32, v0 quad_perm:[1,0,3,2] row_mask:0xf bank_mask:0xf
	s_waitcnt lgkmcnt(0)
	v_add_f32_e32 v0, v0, v32
	s_nop 1
	v_mov_b32_dpp v32, v0 quad_perm:[2,3,0,1] row_mask:0xf bank_mask:0xf
	s_waitcnt lgkmcnt(0)
	v_add_f32_e32 v0, v0, v32
	s_nop 1
	v_mov_b32_dpp v32, v0 row_half_mirror row_mask:0xf bank_mask:0xf
	s_waitcnt lgkmcnt(0)
	v_add_f32_e32 v0, v0, v32
	s_nop 1
	v_mov_b32_dpp v32, v0 row_mirror row_mask:0xf bank_mask:0xf
	s_waitcnt lgkmcnt(0)
; __device__ __forceinline__ unsigned cvtpk(float lo, float hi) { unsigned r; asm volatile("v_cvt_pk_bf16_f32 %0, %1, %2" : "=v"(r) : "v"(lo), "v"(hi)); return r; }
; __device__ __forceinline__ float silu(float z) { return z * __builtin_amdgcn_rcpf(1.0f + __builtin_amdgcn_exp2f(-1.4426950408889634f * z)); }
; template <bool NORM>
; __device__ __forceinline__ void out_rows(const f32x16* o, const float* rli_or_null, char* lds, const float* gain, const float gscale,
;                                          const bf16_t* Z, bf16_t* O, const size_t obase  ) {
;     ...
;   for (int it = 0; it < 8; ++it) { const int row = it * 4 + rsub;
;     f32x4 v0 = *(const f32x4*)(stg + row * STG_LD + c8), v1 = *(const f32x4*)(stg + row * STG_LD + c8 + 4);
;     const size_t off = obase + (size_t)row * 1024 + c8;
;     const u32x4 zv = zq[it];
;     if constexpr (NORM) {
;       float ssq = (v0[0] * v0[0] + v0[1] * v0[1]) + (v0[2] * v0[2] + v0[3] * v0[3]) + (v1[0] * v1[0] + v1[1] * v1[1]) + (v1[2] * v1[2] + v1[3] * v1[3]);
;       ssq += __shfl_xor(ssq, 1); ssq += __shfl_xor(ssq, 2); ssq += __shfl_xor(ssq, 4); ssq += __shfl_xor(ssq, 8);
;       const float rstd = __builtin_amdgcn_rsqf(ssq * (1.0f / 128.0f) + 1e-6f);
;       v0 = v0 * rstd * g0; v1 = v1 * rstd * g1; }
;     v0[0] *= silu(__uint_as_float(zv.x << 16)); v0[1] *= silu(__uint_as_float(zv.x & 0xffff0000u));
;     v0[2] *= silu(__uint_as_float(zv.y << 16)); v0[3] *= silu(__uint_as_float(zv.y & 0xffff0000u));
;     v1[0] *= silu(__uint_as_float(zv.z << 16)); v1[1] *= silu(__uint_as_float(zv.z & 0xffff0000u));
;     v1[2] *= silu(__uint_as_float(zv.w << 16)); v1[3] *= silu(__uint_as_float(zv.w & 0xffff0000u));
;     u32x4 w = {cvtpk(v0[0], v0[1]), cvtpk(v0[2], v0[3]), cvtpk(v1[0], v1[1]), cvtpk(v1[2], v1[3])};
;     __builtin_nontemporal_store(w, (u32x4*)(O + off)); }
	v_add_f32_e32 v0, v0, v32
	v_fmamk_f32 v0, v0, 0x3c000000, v192
	v_rsq_f32_e32 v32, v0
	v_or_b32_e32 v0, 0x6000, v34
	v_lshl_add_u64 v[44:45], v[30:31], 0, v[0:1]
	v_lshlrev_b32_e32 v0, 16, v14
	global_store_dwordx4 v[44:45], v[18:21], off nt
	v_and_b32_e32 v14, 0xffff0000, v14
	s_nop 0
	v_pk_mul_f32 v[18:19], v[22:23], v[32:33] op_sel_hi:[1,0]
	v_pk_mul_f32 v[22:23], v[26:27], v[32:33] op_sel_hi:[1,0]
	v_mul_f32_e32 v26, 0xbfb8aa3b, v0
	v_exp_f32_e32 v26, v26
	v_mul_f32_e32 v27, 0xbfb8aa3b, v14
	v_exp_f32_e32 v27, v27
	v_pk_mul_f32 v[18:19], v[40:41], v[18:19]
	v_add_f32_e32 v26, 1.0, v26
	v_rcp_f32_e32 v26, v26
	v_add_f32_e32 v27, 1.0, v27
	v_rcp_f32_e32 v27, v27
	v_pk_mul_f32 v[20:21], v[24:25], v[32:33] op_sel_hi:[1,0]
	v_mul_f32_e32 v0, v26, v0
	v_mul_f32_e32 v0, v0, v18
	v_lshlrev_b32_e32 v18, 16, v15
	v_and_b32_e32 v15, 0xffff0000, v15
	v_mul_f32_e32 v14, v27, v14
	v_mul_f32_e32 v26, 0xbfb8aa3b, v18
	v_mul_f32_e32 v27, 0xbfb8aa3b, v15
	v_exp_f32_e32 v26, v26
	v_exp_f32_e32 v27, v27
	v_mul_f32_e32 v14, v14, v19
	v_pk_mul_f32 v[24:25], v[28:29], v[32:33] op_sel_hi:[1,0]
	v_add_f32_e32 v19, 1.0, v26
	v_add_f32_e32 v26, 1.0, v27
	v_lshlrev_b32_e32 v27, 16, v16
	v_mul_f32_e32 v28, 0xbfb8aa3b, v27
	v_rcp_f32_e32 v19, v19
	v_exp_f32_e32 v28, v28
	v_pk_mul_f32 v[20:21], v[42:43], v[20:21]
	v_rcp_f32_e32 v26, v26
	v_mul_f32_e32 v18, v19, v18
	v_add_f32_e32 v19, 1.0, v28
	v_and_b32_e32 v16, 0xffff0000, v16
	v_mul_f32_e32 v18, v18, v20
	v_rcp_f32_e32 v19, v19
	v_mul_f32_e32 v20, 0xbfb8aa3b, v16
	v_exp_f32_e32 v20, v20
	v_mul_f32_e32 v15, v26, v15
	v_pk_mul_f32 v[22:23], v[36:37], v[22:23]
	v_mul_f32_e32 v15, v15, v21
	v_mul_f32_e32 v19, v19, v27
	v_lshlrev_b32_e32 v21, 16, v17
	v_and_b32_e32 v17, 0xffff0000, v17
	v_mul_f32_e32 v19, v19, v22
	v_add_f32_e32 v20, 1.0, v20
	v_mul_f32_e32 v22, 0xbfb8aa3b, v21
	v_mul_f32_e32 v26, 0xbfb8aa3b, v17
	v_rcp_f32_e32 v20, v20
	v_exp_f32_e32 v22, v22
	v_exp_f32_e32 v26, v26
	v_pk_mul_f32 v[24:25], v[38:39], v[24:25]
	v_mul_f32_e32 v16, v20, v16
	v_add_f32_e32 v20, 1.0, v22
	v_add_f32_e32 v22, 1.0, v26
	v_rcp_f32_e32 v20, v20
	v_rcp_f32_e32 v22, v22
	v_mul_f32_e32 v16, v16, v23
	v_cvt_pk_bf16_f32 v14, v0, v14
	v_mul_f32_e32 v20, v20, v21
	v_mul_f32_e32 v17, v22, v17
	v_mul_f32_e32 v20, v20, v24
	v_mul_f32_e32 v17, v17, v25
	v_cvt_pk_bf16_f32 v15, v18, v15
	v_cvt_pk_bf16_f32 v16, v19, v16
	v_cvt_pk_bf16_f32 v17, v20, v17
	ds_read_b128 v[18:21], v47 offset:10560
	ds_read_b128 v[22:25], v47 offset:10576
	s_waitcnt lgkmcnt(1)
	v_pk_mul_f32 v[26:27], v[20:21], v[20:21]
	v_pk_mul_f32 v[28:29], v[18:19], v[18:19]
	s_nop 0
	v_pk_mov_b32 v[32:33], v[28:29], v[26:27] op_sel:[1,0]
	v_mov_b32_e32 v29, v27
	v_pk_add_f32 v[26:27], v[32:33], v[28:29]
	s_waitcnt lgkmcnt(0)
	v_pk_mul_f32 v[28:29], v[24:25], v[24:25]
	v_pk_mul_f32 v[32:33], v[22:23], v[22:23]
	v_mov_b32_e32 v44, v28
	v_mov_b32_e32 v45, v32
	v_mov_b32_e32 v32, v29
	v_pk_add_f32 v[28:29], v[44:45], v[32:33]
	v_add_f32_e32 v0, v26, v27
	v_add_f32_e32 v0, v0, v29
	v_add_f32_e32 v0, v28, v0
	s_nop 1
	v_mov_b32_dpp v26, v0 quad_perm:[1,0,3,2] row_mask:0xf bank_mask:0xf
	s_waitcnt lgkmcnt(0)
	v_add_f32_e32 v0, v0, v26
	s_nop 1
	v_mov_b32_dpp v26, v0 quad_perm:[2,3,0,1] row_mask:0xf bank_mask:0xf
	s_waitcnt lgkmcnt(0)
	v_add_f32_e32 v0, v0, v26
	s_nop 1
	v_mov_b32_dpp v26, v0 row_half_mirror row_mask:0xf bank_mask:0xf
	s_waitcnt lgkmcnt(0)
	v_add_f32_e32 v0, v0, v26
	s_nop 1
	v_mov_b32_dpp v26, v0 row_mirror row_mask:0xf bank_mask:0xf
	s_waitcnt lgkmcnt(0)
	v_add_f32_e32 v0, v0, v26
	v_fmamk_f32 v0, v0, 0x3c000000, v192
	v_rsq_f32_e32 v26, v0
	v_or_b32_e32 v0, 0x8000, v34
	v_lshl_add_u64 v[28:29], v[30:31], 0, v[0:1]
	v_lshlrev_b32_e32 v0, 16, v10
	global_store_dwordx4 v[28:29], v[14:17], off nt
	v_and_b32_e32 v10, 0xffff0000, v10
	s_nop 0
	v_pk_mul_f32 v[14:15], v[18:19], v[26:27] op_sel_hi:[1,0]
	v_pk_mul_f32 v[18:19], v[22:23], v[26:27] op_sel_hi:[1,0]
	v_mul_f32_e32 v22, 0xbfb8aa3b, v0
	v_exp_f32_e32 v22, v22
	v_mul_f32_e32 v23, 0xbfb8aa3b, v10
	v_exp_f32_e32 v23, v23
	v_pk_mul_f32 v[14:15], v[40:41], v[14:15]
	v_add_f32_e32 v22, 1.0, v22
	v_rcp_f32_e32 v22, v22
	v_add_f32_e32 v23, 1.0, v23
	v_rcp_f32_e32 v23, v23
	v_pk_mul_f32 v[16:17], v[20:21], v[26:27] op_sel_hi:[1,0]
	v_mul_f32_e32 v0, v22, v0
	v_mul_f32_e32 v0, v0, v14
	v_lshlrev_b32_e32 v14, 16, v11
	v_and_b32_e32 v11, 0xffff0000, v11
	v_mul_f32_e32 v10, v23, v10
	v_mul_f32_e32 v22, 0xbfb8aa3b, v14
	v_mul_f32_e32 v23, 0xbfb8aa3b, v11
	v_exp_f32_e32 v22, v22
	v_exp_f32_e32 v23, v23
	v_mul_f32_e32 v10, v10, v15
	v_pk_mul_f32 v[20:21], v[24:25], v[26:27] op_sel_hi:[1,0]
	v_add_f32_e32 v15, 1.0, v22
	v_add_f32_e32 v22, 1.0, v23
	v_lshlrev_b32_e32 v23, 16, v12
	v_mul_f32_e32 v24, 0xbfb8aa3b, v23
	v_rcp_f32_e32 v15, v15
	v_exp_f32_e32 v24, v24
	v_pk_mul_f32 v[16:17], v[42:43], v[16:17]
	v_rcp_f32_e32 v22, v22
	v_mul_f32_e32 v14, v15, v14
	v_add_f32_e32 v15, 1.0, v24
	v_and_b32_e32 v12, 0xffff0000, v12
	v_mul_f32_e32 v14, v14, v16
	v_rcp_f32_e32 v15, v15
	v_mul_f32_e32 v16, 0xbfb8aa3b, v12
	v_exp_f32_e32 v16, v16
	v_mul_f32_e32 v11, v22, v11
	v_pk_mul_f32 v[18:19], v[36:37], v[18:19]
	v_mul_f32_e32 v11, v11, v17
	v_mul_f32_e32 v15, v15, v23
	v_lshlrev_b32_e32 v17, 16, v13
	v_and_b32_e32 v13, 0xffff0000, v13
	v_mul_f32_e32 v15, v15, v18
	v_add_f32_e32 v16, 1.0, v16
	v_mul_f32_e32 v18, 0xbfb8aa3b, v17
	v_mul_f32_e32 v22, 0xbfb8aa3b, v13
	v_rcp_f32_e32 v16, v16
	v_exp_f32_e32 v18, v18
	v_exp_f32_e32 v22, v22
	v_pk_mul_f32 v[20:21], v[38:39], v[20:21]
	v_mul_f32_e32 v12, v16, v12
	v_add_f32_e32 v16, 1.0, v18
	v_add_f32_e32 v18, 1.0, v22
	v_rcp_f32_e32 v16, v16
	v_rcp_f32_e32 v18, v18
	v_mul_f32_e32 v12, v12, v19
	v_cvt_pk_bf16_f32 v10, v0, v10
	v_mul_f32_e32 v16, v16, v17
	v_mul_f32_e32 v13, v18, v13
	v_mul_f32_e32 v16, v16, v20
	v_mul_f32_e32 v13, v13, v21
	v_cvt_pk_bf16_f32 v11, v14, v11
	v_cvt_pk_bf16_f32 v12, v15, v12
	v_cvt_pk_bf16_f32 v13, v16, v13
	ds_read_b128 v[14:17], v47 offset:12672
	ds_read_b128 v[18:21], v47 offset:12688
	s_waitcnt lgkmcnt(1)
; __device__ __forceinline__ unsigned cvtpk(float lo, float hi) { unsigned r; asm volatile("v_cvt_pk_bf16_f32 %0, %1, %2" : "=v"(r) : "v"(lo), "v"(hi)); return r; }
; __device__ __forceinline__ float silu(float z) { return z * __builtin_amdgcn_rcpf(1.0f + __builtin_amdgcn_exp2f(-1.4426950408889634f * z)); }
; template <bool NORM>
; __device__ __forceinline__ void out_rows(const f32x16* o, const float* rli_or_null, char* lds, const float* gain, const float gscale,
;                                          const bf16_t* Z, bf16_t* O, const size_t obase  ) {
;     ...
;   for (int it = 0; it < 8; ++it) { const int row = it * 4 + rsub;
;     f32x4 v0 = *(const f32x4*)(stg + row * STG_LD + c8), v1 = *(const f32x4*)(stg + row * STG_LD + c8 + 4);
;     const size_t off = obase + (size_t)row * 1024 + c8;
;     const u32x4 zv = zq[it];
;     if constexpr (NORM) {
;       float ssq = (v0[0] * v0[0] + v0[1] * v0[1]) + (v0[2] * v0[2] + v0[3] * v0[3]) + (v1[0] * v1[0] + v1[1] * v1[1]) + (v1[2] * v1[2] + v1[3] * v1[3]);
;       ssq += __shfl_xor(ssq, 1); ssq += __shfl_xor(ssq, 2); ssq += __shfl_xor(ssq, 4); ssq += __shfl_xor(ssq, 8);
;       const float rstd = __builtin_amdgcn_rsqf(ssq * (1.0f / 128.0f) + 1e-6f);
;       v0 = v0 * rstd * g0; v1 = v1 * rstd * g1; }
;     v0[0] *= silu(__uint_as_float(zv.x << 16)); v0[1] *= silu(__uint_as_float(zv.x & 0xffff0000u));
;     v0[2] *= silu(__uint_as_float(zv.y << 16)); v0[3] *= silu(__uint_as_float(zv.y & 0xffff0000u));
;     v1[0] *= silu(__uint_as_float(zv.z << 16)); v1[1] *= silu(__uint_as_float(zv.z & 0xffff0000u));
;     v1[2] *= silu(__uint_as_float(zv.w << 16)); v1[3] *= silu(__uint_as_float(zv.w & 0xffff0000u));
;     u32x4 w = {cvtpk(v0[0], v0[1]), cvtpk(v0[2], v0[3]), cvtpk(v1[0], v1[1]), cvtpk(v1[2], v1[3])};
;     __builtin_nontemporal_store(w, (u32x4*)(O + off)); }
; __device__ __forceinline__ void item_a(bf16_t* OUT, const bf16_t* QA, const bf16_t* KA, const bf16_t* VA, const bf16_t* ZA, const float* tabA, const float* subln, const float lam, ...
;     ...
;   __syncthreads();
;   out_rows<true>(o, nullptr, lds, subln, 0.8f, ZA, OUT, (size_t)(rowbase + qlo) * 1024 + h * 128);
;   __syncthreads();
	v_pk_mul_f32 v[22:23], v[16:17], v[16:17]
	v_pk_mul_f32 v[24:25], v[14:15], v[14:15]
	s_nop 0
	v_pk_mov_b32 v[26:27], v[24:25], v[22:23] op_sel:[1,0]
	v_mov_b32_e32 v25, v23
	v_pk_add_f32 v[22:23], v[26:27], v[24:25]
	s_waitcnt lgkmcnt(0)
	v_pk_mul_f32 v[24:25], v[20:21], v[20:21]
	v_pk_mul_f32 v[26:27], v[18:19], v[18:19]
	v_mov_b32_e32 v28, v24
	v_mov_b32_e32 v29, v26
	v_mov_b32_e32 v26, v25
	v_pk_add_f32 v[24:25], v[28:29], v[26:27]
	v_add_f32_e32 v0, v22, v23
	v_add_f32_e32 v0, v0, v25
	v_add_f32_e32 v0, v24, v0
	s_nop 1
	v_mov_b32_dpp v22, v0 quad_perm:[1,0,3,2] row_mask:0xf bank_mask:0xf
	s_waitcnt lgkmcnt(0)
	v_add_f32_e32 v0, v0, v22
	s_nop 1
	v_mov_b32_dpp v22, v0 quad_perm:[2,3,0,1] row_mask:0xf bank_mask:0xf
	s_waitcnt lgkmcnt(0)
	v_add_f32_e32 v0, v0, v22
	s_nop 1
	v_mov_b32_dpp v22, v0 row_half_mirror row_mask:0xf bank_mask:0xf
	s_waitcnt lgkmcnt(0)
	v_add_f32_e32 v0, v0, v22
	s_nop 1
	v_mov_b32_dpp v22, v0 row_mirror row_mask:0xf bank_mask:0xf
	s_waitcnt lgkmcnt(0)
	v_add_f32_e32 v0, v0, v22
	v_fmamk_f32 v0, v0, 0x3c000000, v192
	v_rsq_f32_e32 v22, v0
	v_or_b32_e32 v0, 0xa000, v34
	v_lshl_add_u64 v[24:25], v[30:31], 0, v[0:1]
	v_lshlrev_b32_e32 v0, 16, v6
	global_store_dwordx4 v[24:25], v[10:13], off nt
	v_and_b32_e32 v6, 0xffff0000, v6
	s_nop 0
	v_pk_mul_f32 v[10:11], v[14:15], v[22:23] op_sel_hi:[1,0]
	v_pk_mul_f32 v[14:15], v[18:19], v[22:23] op_sel_hi:[1,0]
	v_mul_f32_e32 v18, 0xbfb8aa3b, v0
	v_exp_f32_e32 v18, v18
	v_mul_f32_e32 v19, 0xbfb8aa3b, v6
	v_exp_f32_e32 v19, v19
	v_pk_mul_f32 v[10:11], v[40:41], v[10:11]
	v_add_f32_e32 v18, 1.0, v18
	v_rcp_f32_e32 v18, v18
	v_add_f32_e32 v19, 1.0, v19
	v_rcp_f32_e32 v19, v19
	v_pk_mul_f32 v[12:13], v[16:17], v[22:23] op_sel_hi:[1,0]
	v_mul_f32_e32 v0, v18, v0
	v_mul_f32_e32 v0, v0, v10
	v_lshlrev_b32_e32 v10, 16, v7
	v_and_b32_e32 v7, 0xffff0000, v7
	v_mul_f32_e32 v6, v19, v6
	v_mul_f32_e32 v18, 0xbfb8aa3b, v10
	v_mul_f32_e32 v19, 0xbfb8aa3b, v7
	v_exp_f32_e32 v18, v18
	v_exp_f32_e32 v19, v19
	v_mul_f32_e32 v6, v6, v11
	v_pk_mul_f32 v[16:17], v[20:21], v[22:23] op_sel_hi:[1,0]
	v_add_f32_e32 v11, 1.0, v18
	v_add_f32_e32 v18, 1.0, v19
	v_lshlrev_b32_e32 v19, 16, v8
	v_mul_f32_e32 v20, 0xbfb8aa3b, v19
	v_rcp_f32_e32 v11, v11
	v_exp_f32_e32 v20, v20
	v_pk_mul_f32 v[12:13], v[42:43], v[12:13]
	v_rcp_f32_e32 v18, v18
	v_mul_f32_e32 v10, v11, v10
	v_add_f32_e32 v11, 1.0, v20
	v_and_b32_e32 v8, 0xffff0000, v8
	v_mul_f32_e32 v10, v10, v12
	v_rcp_f32_e32 v11, v11
	v_mul_f32_e32 v12, 0xbfb8aa3b, v8
	v_exp_f32_e32 v12, v12
	v_mul_f32_e32 v7, v18, v7
	v_pk_mul_f32 v[14:15], v[36:37], v[14:15]
	v_mul_f32_e32 v7, v7, v13
	v_mul_f32_e32 v11, v11, v19
	v_lshlrev_b32_e32 v13, 16, v9
	v_and_b32_e32 v9, 0xffff0000, v9
	v_mul_f32_e32 v11, v11, v14
	v_add_f32_e32 v12, 1.0, v12
	v_mul_f32_e32 v14, 0xbfb8aa3b, v13
	v_mul_f32_e32 v18, 0xbfb8aa3b, v9
	v_rcp_f32_e32 v12, v12
	v_exp_f32_e32 v14, v14
	v_exp_f32_e32 v18, v18
	v_pk_mul_f32 v[16:17], v[38:39], v[16:17]
	v_mul_f32_e32 v8, v12, v8
	v_add_f32_e32 v12, 1.0, v14
	v_add_f32_e32 v14, 1.0, v18
	v_rcp_f32_e32 v12, v12
	v_rcp_f32_e32 v14, v14
	v_mul_f32_e32 v8, v8, v15
	v_cvt_pk_bf16_f32 v6, v0, v6
	v_mul_f32_e32 v12, v12, v13
	v_mul_f32_e32 v9, v14, v9
	v_mul_f32_e32 v12, v12, v16
	v_mul_f32_e32 v9, v9, v17
	v_cvt_pk_bf16_f32 v7, v10, v7
	v_cvt_pk_bf16_f32 v8, v11, v8
	v_cvt_pk_bf16_f32 v9, v12, v9
	ds_read_b128 v[10:13], v47 offset:14784
	ds_read_b128 v[14:17], v47 offset:14800
	s_waitcnt lgkmcnt(1)
	v_pk_mul_f32 v[18:19], v[12:13], v[12:13]
	v_pk_mul_f32 v[20:21], v[10:11], v[10:11]
	s_nop 0
	v_pk_mov_b32 v[22:23], v[20:21], v[18:19] op_sel:[1,0]
	v_mov_b32_e32 v21, v19
	v_pk_add_f32 v[18:19], v[22:23], v[20:21]
	s_waitcnt lgkmcnt(0)
	v_pk_mul_f32 v[20:21], v[16:17], v[16:17]
	v_pk_mul_f32 v[22:23], v[14:15], v[14:15]
	v_mov_b32_e32 v24, v20
	v_mov_b32_e32 v25, v22
	v_mov_b32_e32 v22, v21
	v_pk_add_f32 v[20:21], v[24:25], v[22:23]
	v_add_f32_e32 v0, v18, v19
	v_add_f32_e32 v0, v0, v21
	v_add_f32_e32 v0, v20, v0
	s_nop 1
	v_mov_b32_dpp v18, v0 quad_perm:[1,0,3,2] row_mask:0xf bank_mask:0xf
	s_waitcnt lgkmcnt(0)
	v_add_f32_e32 v0, v0, v18
	s_nop 1
	v_mov_b32_dpp v18, v0 quad_perm:[2,3,0,1] row_mask:0xf bank_mask:0xf
	s_waitcnt lgkmcnt(0)
	v_add_f32_e32 v0, v0, v18
	s_nop 1
	v_mov_b32_dpp v18, v0 row_half_mirror row_mask:0xf bank_mask:0xf
	s_waitcnt lgkmcnt(0)
	v_add_f32_e32 v0, v0, v18
	s_nop 1
	v_mov_b32_dpp v18, v0 row_mirror row_mask:0xf bank_mask:0xf
	s_waitcnt lgkmcnt(0)
	v_add_f32_e32 v0, v0, v18
	v_fmamk_f32 v0, v0, 0x3c000000, v192
	v_rsq_f32_e32 v18, v0
	v_or_b32_e32 v0, 0xc000, v34
	v_lshl_add_u64 v[20:21], v[30:31], 0, v[0:1]
	v_lshlrev_b32_e32 v0, 16, v2
	global_store_dwordx4 v[20:21], v[6:9], off nt
	v_and_b32_e32 v2, 0xffff0000, v2
	s_nop 0
	v_pk_mul_f32 v[6:7], v[10:11], v[18:19] op_sel_hi:[1,0]
	v_pk_mul_f32 v[10:11], v[14:15], v[18:19] op_sel_hi:[1,0]
	v_mul_f32_e32 v14, 0xbfb8aa3b, v0
	v_exp_f32_e32 v14, v14
	v_mul_f32_e32 v15, 0xbfb8aa3b, v2
	v_exp_f32_e32 v15, v15
	v_pk_mul_f32 v[6:7], v[40:41], v[6:7]
	v_add_f32_e32 v14, 1.0, v14
	v_rcp_f32_e32 v14, v14
	v_add_f32_e32 v15, 1.0, v15
	v_rcp_f32_e32 v15, v15
	v_pk_mul_f32 v[8:9], v[12:13], v[18:19] op_sel_hi:[1,0]
	v_mul_f32_e32 v0, v14, v0
	v_mul_f32_e32 v0, v0, v6
	v_lshlrev_b32_e32 v6, 16, v3
	v_and_b32_e32 v3, 0xffff0000, v3
	v_mul_f32_e32 v2, v15, v2
	v_mul_f32_e32 v14, 0xbfb8aa3b, v6
	v_mul_f32_e32 v15, 0xbfb8aa3b, v3
	v_exp_f32_e32 v14, v14
	v_exp_f32_e32 v15, v15
	v_mul_f32_e32 v2, v2, v7
	v_pk_mul_f32 v[12:13], v[16:17], v[18:19] op_sel_hi:[1,0]
	v_add_f32_e32 v7, 1.0, v14
	v_add_f32_e32 v14, 1.0, v15
	v_lshlrev_b32_e32 v15, 16, v4
	v_mul_f32_e32 v16, 0xbfb8aa3b, v15
	v_rcp_f32_e32 v7, v7
	v_exp_f32_e32 v16, v16
	v_pk_mul_f32 v[8:9], v[42:43], v[8:9]
	v_rcp_f32_e32 v14, v14
	v_mul_f32_e32 v6, v7, v6
	v_add_f32_e32 v7, 1.0, v16
	v_and_b32_e32 v4, 0xffff0000, v4
	v_mul_f32_e32 v6, v6, v8
	v_rcp_f32_e32 v7, v7
	v_mul_f32_e32 v8, 0xbfb8aa3b, v4
	v_exp_f32_e32 v8, v8
	v_mul_f32_e32 v3, v14, v3
	v_pk_mul_f32 v[10:11], v[36:37], v[10:11]
	v_mul_f32_e32 v3, v3, v9
	v_mul_f32_e32 v7, v7, v15
	v_lshlrev_b32_e32 v9, 16, v5
	v_and_b32_e32 v5, 0xffff0000, v5
	v_mul_f32_e32 v7, v7, v10
	v_add_f32_e32 v8, 1.0, v8
	v_mul_f32_e32 v10, 0xbfb8aa3b, v9
	v_mul_f32_e32 v14, 0xbfb8aa3b, v5
	v_rcp_f32_e32 v8, v8
	v_exp_f32_e32 v10, v10
	v_exp_f32_e32 v14, v14
	v_pk_mul_f32 v[12:13], v[38:39], v[12:13]
	v_mul_f32_e32 v4, v8, v4
	v_add_f32_e32 v8, 1.0, v10
	v_add_f32_e32 v10, 1.0, v14
	v_rcp_f32_e32 v10, v10
	v_rcp_f32_e32 v8, v8
	v_mul_f32_e32 v4, v4, v11
	v_cvt_pk_bf16_f32 v2, v0, v2
	v_mul_f32_e32 v5, v10, v5
	v_or_b32_e32 v0, 0xe000, v34
	v_mul_f32_e32 v8, v8, v9
	v_mul_f32_e32 v5, v5, v13
	v_cvt_pk_bf16_f32 v3, v6, v3
	v_cvt_pk_bf16_f32 v4, v7, v4
	v_lshl_add_u64 v[6:7], v[30:31], 0, v[0:1]
	v_mul_f32_e32 v8, v8, v12
	v_cvt_pk_bf16_f32 v5, v8, v5
	global_store_dwordx4 v[6:7], v[2:5], off nt
	s_barrier
	s_cbranch_scc1 .LBB0_206

; __device__ __forceinline__ int crow(int r, int hi) { return (r & 3) + 8 * (r >> 2) + 4 * hi; }
; template <bool NORM>
; __device__ __forceinline__ void out_rows(const f32x16* o, const float* rli_or_null, char* lds, const float* gain, const float gscale,
;                                          const bf16_t* Z, bf16_t* O, const size_t obase  ) {
;   int tid_ = threadIdx.x; asm volatile("" : "+v"(tid_));
;   const int tid = tid_, wid = tid >> 6, lane = tid & 63, r32 = lane & 31, hi = lane >> 5;
;   float* stg = (float*)(lds + wid * STG_WAVE);
;   const int c8 = (lane & 15) * 8, rsub = lane >> 4;
;   u32x4 zq[8];
; #pragma unroll
;   for (int it = 0; it < 8; ++it) zq[it] = __builtin_nontemporal_load((const u32x4*)(Z + obase + (size_t)(it * 4 + rsub) * 1024 + c8));
; #pragma unroll
;   for (int d0 = 0; d0 < 4; ++d0)
; #pragma unroll
;     for (int r = 0; r < 16; ++r) stg[crow(r, hi) * STG_LD + d0 * 32 + r32] = rli_or_null ? o[d0][r] * rli_or_null[r] : o[d0][r];
;   asm volatile("s_waitcnt lgkmcnt(0)" ::: "memory");
;   f32x4 g0 = {1.f, 1.f, 1.f, 1.f}, g1 = {1.f, 1.f, 1.f, 1.f};
;   if constexpr (NORM) { g0 = *(const f32x4*)(gain + c8) * gscale; g1 = *(const f32x4*)(gain + c8 + 4) * gscale; }
; #pragma unroll
;   for (int it = 0; it < 8; ++it) { const int row = it * 4 + rsub;
;     f32x4 v0 = *(const f32x4*)(stg + row * STG_LD + c8), v1 = *(const f32x4*)(stg + row * STG_LD + c8 + 4);
;     const size_t off = obase + (size_t)row * 1024 + c8;
;     const u32x4 zv = zq[it];
;     if constexpr (NORM) {
;       float ssq = (v0[0] * v0[0] + v0[1] * v0[1]) + (v0[2] * v0[2] + v0[3] * v0[3]) + (v1[0] * v1[0] + v1[1] * v1[1]) + (v1[2] * v1[2] + v1[3] * v1[3]);
;       ssq += __shfl_xor(ssq, 1); ssq += __shfl_xor(ssq, 2); ssq += __shfl_xor(ssq, 4); ssq += __shfl_xor(ssq, 8);
.LBB0_305:
	v_mov_b32_e32 v36, v176
	s_waitcnt vmcnt(0)
	s_barrier
	v_ashrrev_i32_e32 v173, 31, v172
	s_movk_i32 s0, 0x4200
	v_lshrrev_b32_e32 v0, 6, v36
	v_mul_lo_u32 v37, v0, s0
	v_lshlrev_b32_e32 v0, 3, v36
	v_lshlrev_b64 v[44:45], 11, v[172:173]
	v_readlane_b32 s0, v249, 34
	v_and_b32_e32 v38, 0x78, v0
	v_lshl_or_b32 v44, s76, 1, v44
	v_readlane_b32 s1, v249, 35
	v_bfe_u32 v40, v36, 4, 2
	v_lshlrev_b32_e32 v0, 1, v38
	v_lshl_add_u64 v[2:3], s[0:1], 0, v[44:45]
	v_lshl_add_u64 v[2:3], v[2:3], 0, v[0:1]
	v_lshlrev_b32_e32 v34, 11, v40
	v_mov_b32_e32 v35, v1
	v_lshl_add_u64 v[2:3], v[2:3], 0, v[34:35]
	s_movk_i32 s0, 0x2000
	v_add_co_u32_e32 v4, vcc, s0, v2
	s_movk_i32 s0, 0x4000
	s_nop 0
	v_addc_co_u32_e32 v5, vcc, 0, v3, vcc
	global_load_dwordx4 v[30:33], v[2:3], off nt
	global_load_dwordx4 v[26:29], v[4:5], off nt
	v_add_co_u32_e32 v4, vcc, s0, v2
	s_movk_i32 s0, 0x6000
	s_nop 0
	v_addc_co_u32_e32 v5, vcc, 0, v3, vcc
	v_add_co_u32_e32 v6, vcc, s0, v2
	s_mov_b32 s0, 0x8000
	s_nop 0
	v_addc_co_u32_e32 v7, vcc, 0, v3, vcc
	global_load_dwordx4 v[22:25], v[4:5], off nt
	global_load_dwordx4 v[18:21], v[6:7], off nt
	v_add_co_u32_e32 v4, vcc, s0, v2
	s_mov_b32 s0, 0xa000
	s_nop 0
	v_addc_co_u32_e32 v5, vcc, 0, v3, vcc
	v_add_co_u32_e32 v6, vcc, s0, v2
	s_mov_b32 s0, 0xc000
	s_nop 0
	v_addc_co_u32_e32 v7, vcc, 0, v3, vcc
	v_and_b32_e32 v39, 31, v36
	v_lshrrev_b32_e32 v36, 3, v36
	global_load_dwordx4 v[14:17], v[4:5], off nt
	global_load_dwordx4 v[10:13], v[6:7], off nt
	v_add_co_u32_e32 v4, vcc, s0, v2
	v_and_b32_e32 v36, 4, v36
	s_nop 0
	v_addc_co_u32_e32 v5, vcc, 0, v3, vcc
	s_mov_b32 s0, 0xe000
	v_add_u32_e32 v41, 0, v37
	v_lshlrev_b32_e32 v37, 2, v39
	v_mul_u32_u24_e32 v36, 0x210, v36
	v_add_co_u32_e32 v2, vcc, s0, v2
	v_add3_u32 v36, v41, v37, v36
	s_nop 0
	v_addc_co_u32_e32 v3, vcc, 0, v3, vcc
	v_add_u32_e32 v37, 0x400, v36
	v_add_u32_e32 v39, 0x1000, v36
	v_add_u32_e32 v42, 0x1400, v36
	v_add_u32_e32 v43, 0x2000, v36
	v_add_u32_e32 v46, 0x2400, v36
	v_add_u32_e32 v48, 0x3200, v36
	global_load_dwordx4 v[6:9], v[4:5], off nt
	s_nop 0
	global_load_dwordx4 v[2:5], v[2:3], off nt
	ds_write2_b32 v36, v80, v96 offset1:32
	ds_write2_b32 v36, v81, v97 offset0:132 offset1:164
	ds_write2_b32 v37, v82, v98 offset0:8 offset1:40
	ds_write2_b32 v37, v83, v99 offset0:140 offset1:172
	ds_write2_b32 v39, v84, v100 offset0:32 offset1:64
	ds_write2_b32 v39, v85, v101 offset0:164 offset1:196
	ds_write2_b32 v42, v86, v102 offset0:40 offset1:72
	ds_write2_b32 v42, v87, v103 offset0:172 offset1:204
	ds_write2_b32 v43, v88, v104 offset0:64 offset1:96
	ds_write2_b32 v43, v89, v105 offset0:196 offset1:228
	ds_write2_b32 v46, v90, v106 offset0:72 offset1:104
	ds_write2_b32 v46, v91, v107 offset0:204 offset1:236
	v_add_u32_e32 v47, 0x3000, v36
	ds_write2_b32 v48, v93, v109 offset0:100 offset1:132
	v_add_u32_e32 v48, 0x3400, v36
	v_add_u32_e32 v49, 0x3600, v36
	ds_write2_b32 v47, v92, v108 offset0:96 offset1:128
	ds_write2_b32 v48, v94, v110 offset0:104 offset1:136
	ds_write2_b32 v49, v95, v111 offset0:108 offset1:140
	ds_write2_b32 v36, v112, v128 offset0:64 offset1:96
	ds_write2_b32 v36, v113, v129 offset0:196 offset1:228
	ds_write2_b32 v37, v114, v130 offset0:72 offset1:104
	ds_write2_b32 v37, v115, v131 offset0:204 offset1:236
	ds_write2_b32 v39, v116, v132 offset0:96 offset1:128
	v_add_u32_e32 v37, 0x1200, v36
	ds_write2_b32 v37, v117, v133 offset0:100 offset1:132
	ds_write2_b32 v42, v118, v134 offset0:104 offset1:136
	v_add_u32_e32 v37, 0x1600, v36
	ds_write2_b32 v37, v119, v135 offset0:108 offset1:140
	ds_write2_b32 v43, v120, v136 offset0:128 offset1:160
	ds_write2_b32 v46, v121, v137 offset0:4 offset1:36
	ds_write2_b32 v46, v122, v138 offset0:136 offset1:168
	v_add_u32_e32 v37, 0x2800, v36
	v_add_u32_e32 v36, 0x3800, v36
	ds_write2_b32 v37, v123, v139 offset0:12 offset1:44
	ds_write2_b32 v47, v124, v140 offset0:160 offset1:192
	ds_write2_b32 v48, v125, v141 offset0:36 offset1:68
	ds_write2_b32 v48, v126, v142 offset0:168 offset1:200
	ds_write2_b32 v36, v127, v143 offset0:44 offset1:76
	s_waitcnt lgkmcnt(0)
	v_lshlrev_b32_e32 v42, 2, v38
	global_load_dwordx4 v[36:39], v42, s[68:69]
	global_load_dwordx4 v[52:55], v42, s[68:69] offset:16
	v_mul_u32_u24_e32 v40, 0x210, v40
	v_add3_u32 v47, v41, v42, v40
	ds_read_b128 v[56:59], v47
	ds_read_b128 v[60:63], v47 offset:16
	v_and_b32_e32 v46, 64, v177
	v_xor_b32_e32 v43, 1, v177
	v_add_u32_e32 v64, 64, v46
	v_cmp_lt_i32_e32 vcc, v43, v64
	s_mov_b32 s0, 0x3f4ccccd
	v_readlane_b32 s44, v248, 50
	v_cndmask_b32_e32 v40, v177, v43, vcc
	v_lshlrev_b32_e32 v46, 2, v40
	s_waitcnt lgkmcnt(1)
	v_pk_mul_f32 v[40:41], v[58:59], v[58:59]
	v_pk_mul_f32 v[42:43], v[56:57], v[56:57]
	v_readlane_b32 s45, v248, 51
	v_pk_mov_b32 v[48:49], v[42:43], v[40:41] op_sel:[1,0]
	v_mov_b32_e32 v43, v41
	v_pk_add_f32 v[40:41], v[48:49], v[42:43]
	s_waitcnt lgkmcnt(0)
	v_pk_mul_f32 v[42:43], v[62:63], v[62:63]
	v_pk_mul_f32 v[48:49], v[60:61], v[60:61]
	v_mov_b32_e32 v50, v42
	v_mov_b32_e32 v51, v48
	v_mov_b32_e32 v48, v43
	v_pk_add_f32 v[42:43], v[50:51], v[48:49]
	v_add_f32_e32 v40, v40, v41
	v_add_f32_e32 v40, v40, v43
	v_add_f32_e32 v40, v42, v40
	s_nop 1
	v_mov_b32_dpp v41, v40 quad_perm:[1,0,3,2] row_mask:0xf bank_mask:0xf
	v_xor_b32_e32 v42, 2, v177
	v_cmp_lt_i32_e32 vcc, v42, v64
	s_waitcnt vmcnt(9)
	v_lshlrev_b32_e32 v51, 16, v30
	v_and_b32_e32 v30, 0xffff0000, v30
	v_cndmask_b32_e32 v42, v177, v42, vcc
	v_lshlrev_b32_e32 v48, 2, v42
	s_waitcnt lgkmcnt(0)
	v_add_f32_e32 v40, v40, v41
	s_nop 1
	v_mov_b32_dpp v41, v40 quad_perm:[2,3,0,1] row_mask:0xf bank_mask:0xf
	v_xor_b32_e32 v42, 4, v177
	v_cmp_lt_i32_e32 vcc, v42, v64
	s_add_i32 s23, s23, s90
	s_waitcnt lgkmcnt(0)
; __device__ __forceinline__ unsigned cvtpk(float lo, float hi) { unsigned r; asm volatile("v_cvt_pk_bf16_f32 %0, %1, %2" : "=v"(r) : "v"(lo), "v"(hi)); return r; }
; __device__ __forceinline__ float silu(float z) { return z * __builtin_amdgcn_rcpf(1.0f + __builtin_amdgcn_exp2f(-1.4426950408889634f * z)); }
; template <bool NORM>
; __device__ __forceinline__ void out_rows(const f32x16* o, const float* rli_or_null, char* lds, const float* gain, const float gscale,
;                                          const bf16_t* Z, bf16_t* O, const size_t obase  ) {
;     ...
;   for (int it = 0; it < 8; ++it) { const int row = it * 4 + rsub;
;     f32x4 v0 = *(const f32x4*)(stg + row * STG_LD + c8), v1 = *(const f32x4*)(stg + row * STG_LD + c8 + 4);
;     const size_t off = obase + (size_t)row * 1024 + c8;
;     const u32x4 zv = zq[it];
;     if constexpr (NORM) {
;       float ssq = (v0[0] * v0[0] + v0[1] * v0[1]) + (v0[2] * v0[2] + v0[3] * v0[3]) + (v1[0] * v1[0] + v1[1] * v1[1]) + (v1[2] * v1[2] + v1[3] * v1[3]);
;       ssq += __shfl_xor(ssq, 1); ssq += __shfl_xor(ssq, 2); ssq += __shfl_xor(ssq, 4); ssq += __shfl_xor(ssq, 8);
;       const float rstd = __builtin_amdgcn_rsqf(ssq * (1.0f / 128.0f) + 1e-6f);
;       v0 = v0 * rstd * g0; v1 = v1 * rstd * g1; }
;     v0[0] *= silu(__uint_as_float(zv.x << 16)); v0[1] *= silu(__uint_as_float(zv.x & 0xffff0000u));
;     v0[2] *= silu(__uint_as_float(zv.y << 16)); v0[3] *= silu(__uint_as_float(zv.y & 0xffff0000u));
;     v1[0] *= silu(__uint_as_float(zv.z << 16)); v1[1] *= silu(__uint_as_float(zv.z & 0xffff0000u));
;     v1[2] *= silu(__uint_as_float(zv.w << 16)); v1[3] *= silu(__uint_as_float(zv.w & 0xffff0000u));
;     u32x4 w = {cvtpk(v0[0], v0[1]), cvtpk(v0[2], v0[3]), cvtpk(v1[0], v1[1]), cvtpk(v1[2], v1[3])};
;     __builtin_nontemporal_store(w, (u32x4*)(O + off)); }
	v_add_f32_e32 v40, v40, v41
	v_cndmask_b32_e32 v42, v177, v42, vcc
	v_lshlrev_b32_e32 v49, 2, v42
	s_nop 1
	v_mov_b32_dpp v41, v40 row_half_mirror row_mask:0xf bank_mask:0xf
	v_xor_b32_e32 v42, 8, v177
	v_cmp_lt_i32_e32 vcc, v42, v64
	s_nop 1
	v_cndmask_b32_e32 v42, v177, v42, vcc
	v_lshlrev_b32_e32 v50, 2, v42
	s_waitcnt lgkmcnt(0)
	v_add_f32_e32 v42, v40, v41
	s_nop 1
	v_mov_b32_dpp v43, v42 row_mirror row_mask:0xf bank_mask:0xf
	s_waitcnt vmcnt(1)
	v_pk_mul_f32 v[40:41], v[36:37], s[0:1] op_sel_hi:[1,0]
	s_waitcnt lgkmcnt(0)
	v_add_f32_e32 v36, v42, v43
	v_fmamk_f32 v36, v36, 0x3c000000, v192
	v_rsq_f32_e32 v64, v36
	s_waitcnt vmcnt(0)
	v_pk_mul_f32 v[36:37], v[52:53], s[0:1] op_sel_hi:[1,0]
	v_pk_mul_f32 v[42:43], v[38:39], s[0:1] op_sel_hi:[1,0]
	v_pk_mul_f32 v[38:39], v[54:55], s[0:1] op_sel_hi:[1,0]
	v_pk_mul_f32 v[52:53], v[56:57], v[64:65] op_sel_hi:[1,0]
	v_pk_mul_f32 v[56:57], v[60:61], v[64:65] op_sel_hi:[1,0]
	v_mul_f32_e32 v60, 0xbfb8aa3b, v51
	v_exp_f32_e32 v60, v60
	v_mul_f32_e32 v61, 0xbfb8aa3b, v30
	v_exp_f32_e32 v61, v61
	v_pk_mul_f32 v[52:53], v[40:41], v[52:53]
	v_add_f32_e32 v60, 1.0, v60
	v_rcp_f32_e32 v60, v60
	v_add_f32_e32 v61, 1.0, v61
	v_rcp_f32_e32 v61, v61
	v_pk_mul_f32 v[54:55], v[58:59], v[64:65] op_sel_hi:[1,0]
	v_mul_f32_e32 v51, v60, v51
	v_mul_f32_e32 v51, v51, v52
	v_lshlrev_b32_e32 v52, 16, v31
	v_and_b32_e32 v31, 0xffff0000, v31
	v_mul_f32_e32 v30, v61, v30
	v_mul_f32_e32 v60, 0xbfb8aa3b, v52
	v_mul_f32_e32 v61, 0xbfb8aa3b, v31
	v_exp_f32_e32 v60, v60
	v_exp_f32_e32 v61, v61
	v_mul_f32_e32 v30, v30, v53
	v_pk_mul_f32 v[58:59], v[62:63], v[64:65] op_sel_hi:[1,0]
	v_add_f32_e32 v53, 1.0, v60
	v_add_f32_e32 v60, 1.0, v61
	v_lshlrev_b32_e32 v61, 16, v32
	v_rcp_f32_e32 v53, v53
	v_mul_f32_e32 v62, 0xbfb8aa3b, v61
	v_exp_f32_e32 v62, v62
	v_pk_mul_f32 v[54:55], v[42:43], v[54:55]
	v_mul_f32_e32 v52, v53, v52
	v_mul_f32_e32 v53, v52, v54
	v_add_f32_e32 v52, 1.0, v62
	v_and_b32_e32 v32, 0xffff0000, v32
	v_rcp_f32_e32 v60, v60
	v_rcp_f32_e32 v52, v52
	v_mul_f32_e32 v54, 0xbfb8aa3b, v32
	v_exp_f32_e32 v54, v54
	v_pk_mul_f32 v[56:57], v[36:37], v[56:57]
	v_mul_f32_e32 v31, v60, v31
	v_mul_f32_e32 v52, v52, v61
	v_mul_f32_e32 v31, v31, v55
	v_mul_f32_e32 v55, v52, v56
	v_add_f32_e32 v52, 1.0, v54
	v_lshlrev_b32_e32 v54, 16, v33
	v_mul_f32_e32 v56, 0xbfb8aa3b, v54
	v_and_b32_e32 v33, 0xffff0000, v33
	v_rcp_f32_e32 v52, v52
	v_exp_f32_e32 v56, v56
	v_mul_f32_e32 v60, 0xbfb8aa3b, v33
	v_exp_f32_e32 v60, v60
	v_mul_f32_e32 v32, v52, v32
	v_add_f32_e32 v52, 1.0, v56
	v_rcp_f32_e32 v52, v52
	v_add_f32_e32 v56, 1.0, v60
	v_rcp_f32_e32 v56, v56
	v_pk_mul_f32 v[58:59], v[38:39], v[58:59]
	v_mul_f32_e32 v52, v52, v54
	v_mul_f32_e32 v32, v32, v57
	v_mul_f32_e32 v57, v52, v58
	v_mul_f32_e32 v33, v56, v33
	v_mul_f32_e32 v33, v33, v59
	v_cvt_pk_bf16_f32 v52, v51, v30
	v_cvt_pk_bf16_f32 v53, v53, v31
	v_cvt_pk_bf16_f32 v54, v55, v32
	v_cvt_pk_bf16_f32 v55, v57, v33
	ds_read_b128 v[56:59], v47 offset:2112
	ds_read_b128 v[60:63], v47 offset:2128
	v_readlane_b32 s0, v248, 54
	s_add_i32 s21, s21, s0
	v_readlane_b32 s0, v248, 47
	s_waitcnt lgkmcnt(1)
	v_pk_mul_f32 v[30:31], v[58:59], v[58:59]
	v_pk_mul_f32 v[32:33], v[56:57], v[56:57]
	s_add_i32 s20, s20, s0
	v_pk_mov_b32 v[64:65], v[32:33], v[30:31] op_sel:[1,0]
	v_mov_b32_e32 v33, v31
	v_pk_add_f32 v[30:31], v[64:65], v[32:33]
	s_waitcnt lgkmcnt(0)
	v_pk_mul_f32 v[32:33], v[62:63], v[62:63]
	v_pk_mul_f32 v[64:65], v[60:61], v[60:61]
	v_mov_b32_e32 v66, v32
	v_mov_b32_e32 v67, v64
	v_mov_b32_e32 v64, v33
	v_pk_add_f32 v[32:33], v[66:67], v[64:65]
	v_add_f32_e32 v30, v30, v31
	v_add_f32_e32 v30, v30, v33
	v_add_f32_e32 v30, v32, v30
	s_nop 1
	v_mov_b32_dpp v31, v30 quad_perm:[1,0,3,2] row_mask:0xf bank_mask:0xf
	v_readlane_b32 s0, v247, 0
	s_cmp_ge_i32 s23, s0
	v_readlane_b32 s1, v248, 55
	s_waitcnt lgkmcnt(0)
	v_add_f32_e32 v30, v30, v31
	s_nop 1
	v_mov_b32_dpp v31, v30 quad_perm:[2,3,0,1] row_mask:0xf bank_mask:0xf
	s_waitcnt lgkmcnt(0)
	v_add_f32_e32 v30, v30, v31
	s_nop 1
	v_mov_b32_dpp v31, v30 row_half_mirror row_mask:0xf bank_mask:0xf
	s_waitcnt lgkmcnt(0)
	v_add_f32_e32 v32, v30, v31
	v_lshl_add_u64 v[30:31], s[44:45], 0, v[44:45]
	s_nop 1
	v_mov_b32_dpp v33, v32 row_mirror row_mask:0xf bank_mask:0xf
	v_lshl_add_u64 v[30:31], v[30:31], 0, v[0:1]
	v_lshlrev_b32_e32 v0, 16, v26
	v_lshl_add_u64 v[44:45], v[30:31], 0, v[34:35]
	v_mul_f32_e32 v35, 0xbfb8aa3b, v0
	v_and_b32_e32 v26, 0xffff0000, v26
	v_exp_f32_e32 v35, v35
	v_mul_f32_e32 v51, 0xbfb8aa3b, v26
	v_exp_f32_e32 v51, v51
	s_waitcnt lgkmcnt(0)
; __device__ __forceinline__ unsigned cvtpk(float lo, float hi) { unsigned r; asm volatile("v_cvt_pk_bf16_f32 %0, %1, %2" : "=v"(r) : "v"(lo), "v"(hi)); return r; }
; __device__ __forceinline__ float silu(float z) { return z * __builtin_amdgcn_rcpf(1.0f + __builtin_amdgcn_exp2f(-1.4426950408889634f * z)); }
; template <bool NORM>
; __device__ __forceinline__ void out_rows(const f32x16* o, const float* rli_or_null, char* lds, const float* gain, const float gscale,
;                                          const bf16_t* Z, bf16_t* O, const size_t obase  ) {
;     ...
;   for (int it = 0; it < 8; ++it) { const int row = it * 4 + rsub;
;     f32x4 v0 = *(const f32x4*)(stg + row * STG_LD + c8), v1 = *(const f32x4*)(stg + row * STG_LD + c8 + 4);
;     const size_t off = obase + (size_t)row * 1024 + c8;
;     const u32x4 zv = zq[it];
;     if constexpr (NORM) {
;       float ssq = (v0[0] * v0[0] + v0[1] * v0[1]) + (v0[2] * v0[2] + v0[3] * v0[3]) + (v1[0] * v1[0] + v1[1] * v1[1]) + (v1[2] * v1[2] + v1[3] * v1[3]);
;       ssq += __shfl_xor(ssq, 1); ssq += __shfl_xor(ssq, 2); ssq += __shfl_xor(ssq, 4); ssq += __shfl_xor(ssq, 8);
;       const float rstd = __builtin_amdgcn_rsqf(ssq * (1.0f / 128.0f) + 1e-6f);
;       v0 = v0 * rstd * g0; v1 = v1 * rstd * g1; }
;     v0[0] *= silu(__uint_as_float(zv.x << 16)); v0[1] *= silu(__uint_as_float(zv.x & 0xffff0000u));
;     v0[2] *= silu(__uint_as_float(zv.y << 16)); v0[3] *= silu(__uint_as_float(zv.y & 0xffff0000u));
;     v1[0] *= silu(__uint_as_float(zv.z << 16)); v1[1] *= silu(__uint_as_float(zv.z & 0xffff0000u));
;     v1[2] *= silu(__uint_as_float(zv.w << 16)); v1[3] *= silu(__uint_as_float(zv.w & 0xffff0000u));
;     u32x4 w = {cvtpk(v0[0], v0[1]), cvtpk(v0[2], v0[3]), cvtpk(v1[0], v1[1]), cvtpk(v1[2], v1[3])};
;     __builtin_nontemporal_store(w, (u32x4*)(O + off)); }
	v_add_f32_e32 v32, v32, v33
	v_fmamk_f32 v32, v32, 0x3c000000, v192
	v_add_f32_e32 v35, 1.0, v35
	v_rsq_f32_e32 v32, v32
	v_rcp_f32_e32 v35, v35
	v_add_f32_e32 v51, 1.0, v51
	v_rcp_f32_e32 v51, v51
	global_store_dwordx4 v[44:45], v[52:55], off nt
	v_pk_mul_f32 v[44:45], v[56:57], v[32:33] op_sel_hi:[1,0]
	v_mul_f32_e32 v0, v35, v0
	v_lshlrev_b32_e32 v35, 16, v27
	v_and_b32_e32 v27, 0xffff0000, v27
	v_pk_mul_f32 v[44:45], v[40:41], v[44:45]
	v_mul_f32_e32 v26, v51, v26
	v_mul_f32_e32 v51, 0xbfb8aa3b, v27
	v_mul_f32_e32 v0, v0, v44
	v_mul_f32_e32 v44, 0xbfb8aa3b, v35
	v_exp_f32_e32 v51, v51
	v_exp_f32_e32 v44, v44
	v_mul_f32_e32 v26, v26, v45
	v_pk_mul_f32 v[52:53], v[58:59], v[32:33] op_sel_hi:[1,0]
	v_add_f32_e32 v45, 1.0, v51
	v_lshlrev_b32_e32 v51, 16, v28
	v_add_f32_e32 v44, 1.0, v44
	v_mul_f32_e32 v56, 0xbfb8aa3b, v51
	v_rcp_f32_e32 v44, v44
	v_exp_f32_e32 v56, v56
	v_rcp_f32_e32 v45, v45
	v_and_b32_e32 v28, 0xffff0000, v28
	v_mul_f32_e32 v35, v44, v35
	v_add_f32_e32 v44, 1.0, v56
	v_mul_f32_e32 v27, v45, v27
	v_rcp_f32_e32 v44, v44
	v_mul_f32_e32 v45, 0xbfb8aa3b, v28
	v_exp_f32_e32 v45, v45
	v_pk_mul_f32 v[52:53], v[42:43], v[52:53]
	v_mul_f32_e32 v44, v44, v51
	v_lshlrev_b32_e32 v51, 16, v29
	v_and_b32_e32 v29, 0xffff0000, v29
	v_mul_f32_e32 v35, v35, v52
	v_mul_f32_e32 v27, v27, v53
	v_add_f32_e32 v45, 1.0, v45
	v_mul_f32_e32 v52, 0xbfb8aa3b, v51
	v_mul_f32_e32 v53, 0xbfb8aa3b, v29
	v_rcp_f32_e32 v45, v45
	v_exp_f32_e32 v52, v52
	v_exp_f32_e32 v53, v53
	v_pk_mul_f32 v[54:55], v[60:61], v[32:33] op_sel_hi:[1,0]
	v_mul_f32_e32 v28, v45, v28
	v_add_f32_e32 v45, 1.0, v52
	v_add_f32_e32 v52, 1.0, v53
	v_rcp_f32_e32 v52, v52
	v_rcp_f32_e32 v45, v45
	v_pk_mul_f32 v[32:33], v[62:63], v[32:33] op_sel_hi:[1,0]
	v_pk_mul_f32 v[54:55], v[36:37], v[54:55]
	v_pk_mul_f32 v[32:33], v[38:39], v[32:33]
	v_mul_f32_e32 v29, v52, v29
	v_mul_f32_e32 v28, v28, v55
	v_mul_f32_e32 v45, v45, v51
	v_mul_f32_e32 v29, v29, v33
	v_mul_f32_e32 v44, v44, v54
	v_mul_f32_e32 v32, v45, v32
	v_cvt_pk_bf16_f32 v26, v0, v26
	v_cvt_pk_bf16_f32 v27, v35, v27
	v_cvt_pk_bf16_f32 v28, v44, v28
	v_cvt_pk_bf16_f32 v29, v32, v29
	ds_read_b128 v[52:55], v47 offset:4224
	ds_read_b128 v[56:59], v47 offset:4240
	s_waitcnt lgkmcnt(1)
	v_pk_mul_f32 v[32:33], v[54:55], v[54:55]
	v_pk_mul_f32 v[44:45], v[52:53], v[52:53]
	s_nop 0
	v_pk_mov_b32 v[60:61], v[44:45], v[32:33] op_sel:[1,0]
	v_mov_b32_e32 v45, v33
	v_pk_add_f32 v[32:33], v[60:61], v[44:45]
	s_waitcnt lgkmcnt(0)
	v_pk_mul_f32 v[44:45], v[58:59], v[58:59]
	v_pk_mul_f32 v[60:61], v[56:57], v[56:57]
	v_mov_b32_e32 v62, v44
	v_mov_b32_e32 v63, v60
	v_mov_b32_e32 v60, v45
	v_pk_add_f32 v[44:45], v[62:63], v[60:61]
	v_add_f32_e32 v0, v32, v33
	v_add_f32_e32 v0, v0, v45
	v_add_f32_e32 v0, v44, v0
	s_nop 1
	v_mov_b32_dpp v32, v0 quad_perm:[1,0,3,2] row_mask:0xf bank_mask:0xf
	s_waitcnt lgkmcnt(0)
	v_add_f32_e32 v0, v0, v32
	s_nop 1
	v_mov_b32_dpp v32, v0 quad_perm:[2,3,0,1] row_mask:0xf bank_mask:0xf
	s_waitcnt lgkmcnt(0)
	v_add_f32_e32 v0, v0, v32
	s_nop 1
	v_mov_b32_dpp v32, v0 row_half_mirror row_mask:0xf bank_mask:0xf
	s_waitcnt lgkmcnt(0)
	v_add_f32_e32 v0, v0, v32
	s_nop 1
	v_mov_b32_dpp v32, v0 row_mirror row_mask:0xf bank_mask:0xf
	s_waitcnt lgkmcnt(0)
	v_add_f32_e32 v0, v0, v32
	v_fmamk_f32 v0, v0, 0x3c000000, v192
	v_rsq_f32_e32 v32, v0
	v_or_b32_e32 v0, 0x2000, v34
	v_lshl_add_u64 v[44:45], v[30:31], 0, v[0:1]
	v_lshlrev_b32_e32 v0, 16, v22
	v_mul_f32_e32 v35, 0xbfb8aa3b, v0
	v_exp_f32_e32 v35, v35
	v_and_b32_e32 v22, 0xffff0000, v22
	v_mul_f32_e32 v51, 0xbfb8aa3b, v22
	v_exp_f32_e32 v51, v51
	v_add_f32_e32 v35, 1.0, v35
	v_rcp_f32_e32 v35, v35
	global_store_dwordx4 v[44:45], v[26:29], off nt
	v_add_f32_e32 v51, 1.0, v51
	v_rcp_f32_e32 v51, v51
	v_pk_mul_f32 v[26:27], v[52:53], v[32:33] op_sel_hi:[1,0]
	v_mul_f32_e32 v0, v35, v0
	v_pk_mul_f32 v[26:27], v[40:41], v[26:27]
	v_mul_f32_e32 v22, v51, v22
	v_mul_f32_e32 v0, v0, v26
	v_lshlrev_b32_e32 v26, 16, v23
	v_and_b32_e32 v23, 0xffff0000, v23
	v_mul_f32_e32 v35, 0xbfb8aa3b, v26
	v_mul_f32_e32 v51, 0xbfb8aa3b, v23
	v_exp_f32_e32 v35, v35
	v_exp_f32_e32 v51, v51
	v_mul_f32_e32 v22, v22, v27
	v_pk_mul_f32 v[28:29], v[54:55], v[32:33] op_sel_hi:[1,0]
	v_add_f32_e32 v27, 1.0, v35
	v_add_f32_e32 v35, 1.0, v51
	v_lshlrev_b32_e32 v51, 16, v24
	v_mul_f32_e32 v52, 0xbfb8aa3b, v51
	v_rcp_f32_e32 v27, v27
	v_exp_f32_e32 v52, v52
	v_pk_mul_f32 v[28:29], v[42:43], v[28:29]
	v_rcp_f32_e32 v35, v35
	v_mul_f32_e32 v26, v27, v26
	v_add_f32_e32 v27, 1.0, v52
	v_and_b32_e32 v24, 0xffff0000, v24
	v_mul_f32_e32 v26, v26, v28
	v_rcp_f32_e32 v27, v27
	v_mul_f32_e32 v28, 0xbfb8aa3b, v24
	v_exp_f32_e32 v28, v28
	v_pk_mul_f32 v[44:45], v[56:57], v[32:33] op_sel_hi:[1,0]
	v_mul_f32_e32 v23, v35, v23
	v_pk_mul_f32 v[44:45], v[36:37], v[44:45]
	v_mul_f32_e32 v23, v23, v29
	v_mul_f32_e32 v27, v27, v51
	v_lshlrev_b32_e32 v29, 16, v25
	v_and_b32_e32 v25, 0xffff0000, v25
	v_mul_f32_e32 v27, v27, v44
	v_add_f32_e32 v28, 1.0, v28
	v_mul_f32_e32 v35, 0xbfb8aa3b, v29
	v_mul_f32_e32 v44, 0xbfb8aa3b, v25
	v_rcp_f32_e32 v28, v28
	v_exp_f32_e32 v35, v35
	v_exp_f32_e32 v44, v44
	v_pk_mul_f32 v[32:33], v[58:59], v[32:33] op_sel_hi:[1,0]
	v_mul_f32_e32 v24, v28, v24
	v_add_f32_e32 v28, 1.0, v35
	v_add_f32_e32 v35, 1.0, v44
	v_rcp_f32_e32 v28, v28
	v_rcp_f32_e32 v35, v35
	v_pk_mul_f32 v[32:33], v[38:39], v[32:33]
	v_mul_f32_e32 v24, v24, v45
	v_mul_f32_e32 v28, v28, v29
	v_mul_f32_e32 v25, v35, v25
	v_mul_f32_e32 v28, v28, v32
	v_mul_f32_e32 v25, v25, v33
	v_cvt_pk_bf16_f32 v22, v0, v22
	v_cvt_pk_bf16_f32 v23, v26, v23
	v_cvt_pk_bf16_f32 v24, v27, v24
	v_cvt_pk_bf16_f32 v25, v28, v25
	ds_read_b128 v[26:29], v47 offset:6336
	ds_read_b128 v[52:55], v47 offset:6352
	s_waitcnt lgkmcnt(1)
; __device__ __forceinline__ unsigned cvtpk(float lo, float hi) { unsigned r; asm volatile("v_cvt_pk_bf16_f32 %0, %1, %2" : "=v"(r) : "v"(lo), "v"(hi)); return r; }
; __device__ __forceinline__ float silu(float z) { return z * __builtin_amdgcn_rcpf(1.0f + __builtin_amdgcn_exp2f(-1.4426950408889634f * z)); }
; template <bool NORM>
; __device__ __forceinline__ void out_rows(const f32x16* o, const float* rli_or_null, char* lds, const float* gain, const float gscale,
;                                          const bf16_t* Z, bf16_t* O, const size_t obase  ) {
;     ...
;   for (int it = 0; it < 8; ++it) { const int row = it * 4 + rsub;
;     f32x4 v0 = *(const f32x4*)(stg + row * STG_LD + c8), v1 = *(const f32x4*)(stg + row * STG_LD + c8 + 4);
;     const size_t off = obase + (size_t)row * 1024 + c8;
;     const u32x4 zv = zq[it];
;     if constexpr (NORM) {
;       float ssq = (v0[0] * v0[0] + v0[1] * v0[1]) + (v0[2] * v0[2] + v0[3] * v0[3]) + (v1[0] * v1[0] + v1[1] * v1[1]) + (v1[2] * v1[2] + v1[3] * v1[3]);
;       ssq += __shfl_xor(ssq, 1); ssq += __shfl_xor(ssq, 2); ssq += __shfl_xor(ssq, 4); ssq += __shfl_xor(ssq, 8);
;       const float rstd = __builtin_amdgcn_rsqf(ssq * (1.0f / 128.0f) + 1e-6f);
;       v0 = v0 * rstd * g0; v1 = v1 * rstd * g1; }
;     v0[0] *= silu(__uint_as_float(zv.x << 16)); v0[1] *= silu(__uint_as_float(zv.x & 0xffff0000u));
;     v0[2] *= silu(__uint_as_float(zv.y << 16)); v0[3] *= silu(__uint_as_float(zv.y & 0xffff0000u));
;     v1[0] *= silu(__uint_as_float(zv.z << 16)); v1[1] *= silu(__uint_as_float(zv.z & 0xffff0000u));
;     v1[2] *= silu(__uint_as_float(zv.w << 16)); v1[3] *= silu(__uint_as_float(zv.w & 0xffff0000u));
;     u32x4 w = {cvtpk(v0[0], v0[1]), cvtpk(v0[2], v0[3]), cvtpk(v1[0], v1[1]), cvtpk(v1[2], v1[3])};
;     __builtin_nontemporal_store(w, (u32x4*)(O + off)); }
	v_pk_mul_f32 v[32:33], v[28:29], v[28:29]
	v_pk_mul_f32 v[44:45], v[26:27], v[26:27]
	s_nop 0
	v_pk_mov_b32 v[56:57], v[44:45], v[32:33] op_sel:[1,0]
	v_mov_b32_e32 v45, v33
	v_pk_add_f32 v[32:33], v[56:57], v[44:45]
	s_waitcnt lgkmcnt(0)
	v_pk_mul_f32 v[44:45], v[54:55], v[54:55]
	v_pk_mul_f32 v[56:57], v[52:53], v[52:53]
	v_mov_b32_e32 v58, v44
	v_mov_b32_e32 v59, v56
	v_mov_b32_e32 v56, v45
	v_pk_add_f32 v[44:45], v[58:59], v[56:57]
	v_add_f32_e32 v0, v32, v33
	v_add_f32_e32 v0, v0, v45
	v_add_f32_e32 v0, v44, v0
	s_nop 1
	v_mov_b32_dpp v32, v0 quad_perm:[1,0,3,2] row_mask:0xf bank_mask:0xf
	s_waitcnt lgkmcnt(0)
	v_add_f32_e32 v0, v0, v32
	s_nop 1
	v_mov_b32_dpp v32, v0 quad_perm:[2,3,0,1] row_mask:0xf bank_mask:0xf
	s_waitcnt lgkmcnt(0)
	v_add_f32_e32 v0, v0, v32
	s_nop 1
	v_mov_b32_dpp v32, v0 row_half_mirror row_mask:0xf bank_mask:0xf
	s_waitcnt lgkmcnt(0)
	v_add_f32_e32 v0, v0, v32
	s_nop 1
	v_mov_b32_dpp v32, v0 row_mirror row_mask:0xf bank_mask:0xf
	s_waitcnt lgkmcnt(0)
	v_add_f32_e32 v0, v0, v32
	v_fmamk_f32 v0, v0, 0x3c000000, v192
	v_rsq_f32_e32 v32, v0
	v_or_b32_e32 v0, 0x4000, v34
	v_lshl_add_u64 v[44:45], v[30:31], 0, v[0:1]
	v_lshlrev_b32_e32 v0, 16, v18
	global_store_dwordx4 v[44:45], v[22:25], off nt
	v_and_b32_e32 v18, 0xffff0000, v18
	s_nop 0
	v_pk_mul_f32 v[22:23], v[26:27], v[32:33] op_sel_hi:[1,0]
	v_pk_mul_f32 v[24:25], v[28:29], v[32:33] op_sel_hi:[1,0]
	v_pk_mul_f32 v[26:27], v[52:53], v[32:33] op_sel_hi:[1,0]
	v_pk_mul_f32 v[28:29], v[54:55], v[32:33] op_sel_hi:[1,0]
	v_mul_f32_e32 v32, 0xbfb8aa3b, v0
	v_exp_f32_e32 v32, v32
	v_mul_f32_e32 v33, 0xbfb8aa3b, v18
	v_exp_f32_e32 v33, v33
	v_pk_mul_f32 v[22:23], v[40:41], v[22:23]
	v_add_f32_e32 v32, 1.0, v32
	v_rcp_f32_e32 v32, v32
	v_add_f32_e32 v33, 1.0, v33
	v_rcp_f32_e32 v33, v33
	v_pk_mul_f32 v[24:25], v[42:43], v[24:25]
	v_mul_f32_e32 v0, v32, v0
	v_mul_f32_e32 v0, v0, v22
	v_lshlrev_b32_e32 v22, 16, v19
	v_and_b32_e32 v19, 0xffff0000, v19
	v_mul_f32_e32 v18, v33, v18
	v_mul_f32_e32 v32, 0xbfb8aa3b, v22
	v_mul_f32_e32 v33, 0xbfb8aa3b, v19
	v_exp_f32_e32 v32, v32
	v_exp_f32_e32 v33, v33
	v_mul_f32_e32 v18, v18, v23
	v_pk_mul_f32 v[26:27], v[36:37], v[26:27]
	v_add_f32_e32 v23, 1.0, v32
	v_add_f32_e32 v32, 1.0, v33
	v_lshlrev_b32_e32 v33, 16, v20
	v_mul_f32_e32 v35, 0xbfb8aa3b, v33
	v_rcp_f32_e32 v23, v23
	v_exp_f32_e32 v35, v35
	v_rcp_f32_e32 v32, v32
	v_and_b32_e32 v20, 0xffff0000, v20
	v_mul_f32_e32 v22, v23, v22
	v_add_f32_e32 v23, 1.0, v35
	v_mul_f32_e32 v22, v22, v24
	v_rcp_f32_e32 v23, v23
	v_mul_f32_e32 v24, 0xbfb8aa3b, v20
	v_exp_f32_e32 v24, v24
	v_mul_f32_e32 v19, v32, v19
	v_mul_f32_e32 v19, v19, v25
	v_mul_f32_e32 v23, v23, v33
	v_lshlrev_b32_e32 v25, 16, v21
	v_and_b32_e32 v21, 0xffff0000, v21
	v_mul_f32_e32 v23, v23, v26
	v_add_f32_e32 v24, 1.0, v24
	v_mul_f32_e32 v26, 0xbfb8aa3b, v25
	v_mul_f32_e32 v32, 0xbfb8aa3b, v21
	v_rcp_f32_e32 v24, v24
	v_exp_f32_e32 v26, v26
	v_exp_f32_e32 v32, v32
	v_pk_mul_f32 v[28:29], v[38:39], v[28:29]
	v_mul_f32_e32 v20, v24, v20
	v_add_f32_e32 v24, 1.0, v26
	v_add_f32_e32 v26, 1.0, v32
	v_rcp_f32_e32 v24, v24
	v_rcp_f32_e32 v26, v26
	v_mul_f32_e32 v20, v20, v27
	v_cvt_pk_bf16_f32 v18, v0, v18
	v_mul_f32_e32 v24, v24, v25
	v_mul_f32_e32 v21, v26, v21
	v_mul_f32_e32 v24, v24, v28
	v_mul_f32_e32 v21, v21, v29
	v_cvt_pk_bf16_f32 v19, v22, v19
	v_cvt_pk_bf16_f32 v20, v23, v20
	v_cvt_pk_bf16_f32 v21, v24, v21
	ds_read_b128 v[22:25], v47 offset:8448
	ds_read_b128 v[26:29], v47 offset:8464
	s_waitcnt lgkmcnt(1)
	v_pk_mul_f32 v[32:33], v[24:25], v[24:25]
	v_pk_mul_f32 v[44:45], v[22:23], v[22:23]
	s_nop 0
	v_pk_mov_b32 v[52:53], v[44:45], v[32:33] op_sel:[1,0]
	v_mov_b32_e32 v45, v33
	v_pk_add_f32 v[32:33], v[52:53], v[44:45]
	s_waitcnt lgkmcnt(0)
	v_pk_mul_f32 v[44:45], v[28:29], v[28:29]
	v_pk_mul_f32 v[52:53], v[26:27], v[26:27]
	v_mov_b32_e32 v54, v44
	v_mov_b32_e32 v55, v52
	v_mov_b32_e32 v52, v45
	v_pk_add_f32 v[44:45], v[54:55], v[52:53]
	v_add_f32_e32 v0, v32, v33
	v_add_f32_e32 v0, v0, v45
	v_add_f32_e32 v0, v44, v0
	s_nop 1
	v_mov_b32_dpp v32, v0 quad_perm:[1,0,3,2] row_mask:0xf bank_mask:0xf
	s_waitcnt lgkmcnt(0)
	v_add_f32_e32 v0, v0, v32
	s_nop 1
	v_mov_b32_dpp v32, v0 quad_perm:[2,3,0,1] row_mask:0xf bank_mask:0xf
	s_waitcnt lgkmcnt(0)
	v_add_f32_e32 v0, v0, v32
	s_nop 1
	v_mov_b32_dpp v32, v0 row_half_mirror row_mask:0xf bank_mask:0xf
	s_waitcnt lgkmcnt(0)
	v_add_f32_e32 v0, v0, v32
	s_nop 1
	v_mov_b32_dpp v32, v0 row_mirror row_mask:0xf bank_mask:0xf
	s_waitcnt lgkmcnt(0)
; __device__ __forceinline__ unsigned cvtpk(float lo, float hi) { unsigned r; asm volatile("v_cvt_pk_bf16_f32 %0, %1, %2" : "=v"(r) : "v"(lo), "v"(hi)); return r; }
; __device__ __forceinline__ float silu(float z) { return z * __builtin_amdgcn_rcpf(1.0f + __builtin_amdgcn_exp2f(-1.4426950408889634f * z)); }
; template <bool NORM>
; __device__ __forceinline__ void out_rows(const f32x16* o, const float* rli_or_null, char* lds, const float* gain, const float gscale,
;                                          const bf16_t* Z, bf16_t* O, const size_t obase  ) {
;     ...
;   for (int it = 0; it < 8; ++it) { const int row = it * 4 + rsub;
;     f32x4 v0 = *(const f32x4*)(stg + row * STG_LD + c8), v1 = *(const f32x4*)(stg + row * STG_LD + c8 + 4);
;     const size_t off = obase + (size_t)row * 1024 + c8;
;     const u32x4 zv = zq[it];
;     if constexpr (NORM) {
;       float ssq = (v0[0] * v0[0] + v0[1] * v0[1]) + (v0[2] * v0[2] + v0[3] * v0[3]) + (v1[0] * v1[0] + v1[1] * v1[1]) + (v1[2] * v1[2] + v1[3] * v1[3]);
;       ssq += __shfl_xor(ssq, 1); ssq += __shfl_xor(ssq, 2); ssq += __shfl_xor(ssq, 4); ssq += __shfl_xor(ssq, 8);
;       const float rstd = __builtin_amdgcn_rsqf(ssq * (1.0f / 128.0f) + 1e-6f);
;       v0 = v0 * rstd * g0; v1 = v1 * rstd * g1; }
;     v0[0] *= silu(__uint_as_float(zv.x << 16)); v0[1] *= silu(__uint_as_float(zv.x & 0xffff0000u));
;     v0[2] *= silu(__uint_as_float(zv.y << 16)); v0[3] *= silu(__uint_as_float(zv.y & 0xffff0000u));
;     v1[0] *= silu(__uint_as_float(zv.z << 16)); v1[1] *= silu(__uint_as_float(zv.z & 0xffff0000u));
;     v1[2] *= silu(__uint_as_float(zv.w << 16)); v1[3] *= silu(__uint_as_float(zv.w & 0xffff0000u));
;     u32x4 w = {cvtpk(v0[0], v0[1]), cvtpk(v0[2], v0[3]), cvtpk(v1[0], v1[1]), cvtpk(v1[2], v1[3])};
;     __builtin_nontemporal_store(w, (u32x4*)(O + off)); }
	v_add_f32_e32 v0, v0, v32
	v_fmamk_f32 v0, v0, 0x3c000000, v192
	v_rsq_f32_e32 v32, v0
	v_or_b32_e32 v0, 0x6000, v34
	v_lshl_add_u64 v[44:45], v[30:31], 0, v[0:1]
	v_lshlrev_b32_e32 v0, 16, v14
	global_store_dwordx4 v[44:45], v[18:21], off nt
	v_and_b32_e32 v14, 0xffff0000, v14
	s_nop 0
	v_pk_mul_f32 v[18:19], v[22:23], v[32:33] op_sel_hi:[1,0]
	v_pk_mul_f32 v[22:23], v[26:27], v[32:33] op_sel_hi:[1,0]
	v_mul_f32_e32 v26, 0xbfb8aa3b, v0
	v_exp_f32_e32 v26, v26
	v_mul_f32_e32 v27, 0xbfb8aa3b, v14
	v_exp_f32_e32 v27, v27
	v_pk_mul_f32 v[18:19], v[40:41], v[18:19]
	v_add_f32_e32 v26, 1.0, v26
	v_rcp_f32_e32 v26, v26
	v_add_f32_e32 v27, 1.0, v27
	v_rcp_f32_e32 v27, v27
	v_pk_mul_f32 v[20:21], v[24:25], v[32:33] op_sel_hi:[1,0]
	v_mul_f32_e32 v0, v26, v0
	v_mul_f32_e32 v0, v0, v18
	v_lshlrev_b32_e32 v18, 16, v15
	v_and_b32_e32 v15, 0xffff0000, v15
	v_mul_f32_e32 v14, v27, v14
	v_mul_f32_e32 v26, 0xbfb8aa3b, v18
	v_mul_f32_e32 v27, 0xbfb8aa3b, v15
	v_exp_f32_e32 v26, v26
	v_exp_f32_e32 v27, v27
	v_mul_f32_e32 v14, v14, v19
	v_pk_mul_f32 v[24:25], v[28:29], v[32:33] op_sel_hi:[1,0]
	v_add_f32_e32 v19, 1.0, v26
	v_add_f32_e32 v26, 1.0, v27
	v_lshlrev_b32_e32 v27, 16, v16
	v_mul_f32_e32 v28, 0xbfb8aa3b, v27
	v_rcp_f32_e32 v19, v19
	v_exp_f32_e32 v28, v28
	v_pk_mul_f32 v[20:21], v[42:43], v[20:21]
	v_rcp_f32_e32 v26, v26
	v_mul_f32_e32 v18, v19, v18
	v_add_f32_e32 v19, 1.0, v28
	v_and_b32_e32 v16, 0xffff0000, v16
	v_mul_f32_e32 v18, v18, v20
	v_rcp_f32_e32 v19, v19
	v_mul_f32_e32 v20, 0xbfb8aa3b, v16
	v_exp_f32_e32 v20, v20
	v_mul_f32_e32 v15, v26, v15
	v_pk_mul_f32 v[22:23], v[36:37], v[22:23]
	v_mul_f32_e32 v15, v15, v21
	v_mul_f32_e32 v19, v19, v27
	v_lshlrev_b32_e32 v21, 16, v17
	v_and_b32_e32 v17, 0xffff0000, v17
	v_mul_f32_e32 v19, v19, v22
	v_add_f32_e32 v20, 1.0, v20
	v_mul_f32_e32 v22, 0xbfb8aa3b, v21
	v_mul_f32_e32 v26, 0xbfb8aa3b, v17
	v_rcp_f32_e32 v20, v20
	v_exp_f32_e32 v22, v22
	v_exp_f32_e32 v26, v26
	v_pk_mul_f32 v[24:25], v[38:39], v[24:25]
	v_mul_f32_e32 v16, v20, v16
	v_add_f32_e32 v20, 1.0, v22
	v_add_f32_e32 v22, 1.0, v26
	v_rcp_f32_e32 v20, v20
	v_rcp_f32_e32 v22, v22
	v_mul_f32_e32 v16, v16, v23
	v_cvt_pk_bf16_f32 v14, v0, v14
	v_mul_f32_e32 v20, v20, v21
	v_mul_f32_e32 v17, v22, v17
	v_mul_f32_e32 v20, v20, v24
	v_mul_f32_e32 v17, v17, v25
	v_cvt_pk_bf16_f32 v15, v18, v15
	v_cvt_pk_bf16_f32 v16, v19, v16
	v_cvt_pk_bf16_f32 v17, v20, v17
	ds_read_b128 v[18:21], v47 offset:10560
	ds_read_b128 v[22:25], v47 offset:10576
	s_waitcnt lgkmcnt(1)
	v_pk_mul_f32 v[26:27], v[20:21], v[20:21]
	v_pk_mul_f32 v[28:29], v[18:19], v[18:19]
	s_nop 0
	v_pk_mov_b32 v[32:33], v[28:29], v[26:27] op_sel:[1,0]
	v_mov_b32_e32 v29, v27
	v_pk_add_f32 v[26:27], v[32:33], v[28:29]
	s_waitcnt lgkmcnt(0)
	v_pk_mul_f32 v[28:29], v[24:25], v[24:25]
	v_pk_mul_f32 v[32:33], v[22:23], v[22:23]
	v_mov_b32_e32 v44, v28
	v_mov_b32_e32 v45, v32
	v_mov_b32_e32 v32, v29
	v_pk_add_f32 v[28:29], v[44:45], v[32:33]
	v_add_f32_e32 v0, v26, v27
	v_add_f32_e32 v0, v0, v29
	v_add_f32_e32 v0, v28, v0
	s_nop 1
	v_mov_b32_dpp v26, v0 quad_perm:[1,0,3,2] row_mask:0xf bank_mask:0xf
	s_waitcnt lgkmcnt(0)
	v_add_f32_e32 v0, v0, v26
	s_nop 1
	v_mov_b32_dpp v26, v0 quad_perm:[2,3,0,1] row_mask:0xf bank_mask:0xf
	s_waitcnt lgkmcnt(0)
	v_add_f32_e32 v0, v0, v26
	s_nop 1
	v_mov_b32_dpp v26, v0 row_half_mirror row_mask:0xf bank_mask:0xf
	s_waitcnt lgkmcnt(0)
	v_add_f32_e32 v0, v0, v26
	s_nop 1
	v_mov_b32_dpp v26, v0 row_mirror row_mask:0xf bank_mask:0xf
	s_waitcnt lgkmcnt(0)
	v_add_f32_e32 v0, v0, v26
	v_fmamk_f32 v0, v0, 0x3c000000, v192
	v_rsq_f32_e32 v26, v0
	v_or_b32_e32 v0, 0x8000, v34
	v_lshl_add_u64 v[28:29], v[30:31], 0, v[0:1]
	v_lshlrev_b32_e32 v0, 16, v10
	global_store_dwordx4 v[28:29], v[14:17], off nt
	v_and_b32_e32 v10, 0xffff0000, v10
	s_nop 0
	v_pk_mul_f32 v[14:15], v[18:19], v[26:27] op_sel_hi:[1,0]
	v_pk_mul_f32 v[18:19], v[22:23], v[26:27] op_sel_hi:[1,0]
	v_mul_f32_e32 v22, 0xbfb8aa3b, v0
	v_exp_f32_e32 v22, v22
	v_mul_f32_e32 v23, 0xbfb8aa3b, v10
	v_exp_f32_e32 v23, v23
	v_pk_mul_f32 v[14:15], v[40:41], v[14:15]
	v_add_f32_e32 v22, 1.0, v22
	v_rcp_f32_e32 v22, v22
	v_add_f32_e32 v23, 1.0, v23
	v_rcp_f32_e32 v23, v23
	v_pk_mul_f32 v[16:17], v[20:21], v[26:27] op_sel_hi:[1,0]
	v_mul_f32_e32 v0, v22, v0
	v_mul_f32_e32 v0, v0, v14
	v_lshlrev_b32_e32 v14, 16, v11
	v_and_b32_e32 v11, 0xffff0000, v11
	v_mul_f32_e32 v10, v23, v10
	v_mul_f32_e32 v22, 0xbfb8aa3b, v14
	v_mul_f32_e32 v23, 0xbfb8aa3b, v11
	v_exp_f32_e32 v22, v22
	v_exp_f32_e32 v23, v23
	v_mul_f32_e32 v10, v10, v15
	v_pk_mul_f32 v[20:21], v[24:25], v[26:27] op_sel_hi:[1,0]
	v_add_f32_e32 v15, 1.0, v22
	v_add_f32_e32 v22, 1.0, v23
	v_lshlrev_b32_e32 v23, 16, v12
	v_mul_f32_e32 v24, 0xbfb8aa3b, v23
	v_rcp_f32_e32 v15, v15
	v_exp_f32_e32 v24, v24
	v_pk_mul_f32 v[16:17], v[42:43], v[16:17]
	v_rcp_f32_e32 v22, v22
	v_mul_f32_e32 v14, v15, v14
	v_add_f32_e32 v15, 1.0, v24
	v_and_b32_e32 v12, 0xffff0000, v12
	v_mul_f32_e32 v14, v14, v16
	v_rcp_f32_e32 v15, v15
	v_mul_f32_e32 v16, 0xbfb8aa3b, v12
	v_exp_f32_e32 v16, v16
	v_mul_f32_e32 v11, v22, v11
	v_pk_mul_f32 v[18:19], v[36:37], v[18:19]
	v_mul_f32_e32 v11, v11, v17
	v_mul_f32_e32 v15, v15, v23
	v_lshlrev_b32_e32 v17, 16, v13
	v_and_b32_e32 v13, 0xffff0000, v13
	v_mul_f32_e32 v15, v15, v18
	v_add_f32_e32 v16, 1.0, v16
	v_mul_f32_e32 v18, 0xbfb8aa3b, v17
	v_mul_f32_e32 v22, 0xbfb8aa3b, v13
	v_rcp_f32_e32 v16, v16
	v_exp_f32_e32 v18, v18
	v_exp_f32_e32 v22, v22
	v_pk_mul_f32 v[20:21], v[38:39], v[20:21]
	v_mul_f32_e32 v12, v16, v12
	v_add_f32_e32 v16, 1.0, v18
	v_add_f32_e32 v18, 1.0, v22
	v_rcp_f32_e32 v16, v16
	v_rcp_f32_e32 v18, v18
	v_mul_f32_e32 v12, v12, v19
	v_cvt_pk_bf16_f32 v10, v0, v10
	v_mul_f32_e32 v16, v16, v17
	v_mul_f32_e32 v13, v18, v13
	v_mul_f32_e32 v16, v16, v20
	v_mul_f32_e32 v13, v13, v21
	v_cvt_pk_bf16_f32 v11, v14, v11
	v_cvt_pk_bf16_f32 v12, v15, v12
	v_cvt_pk_bf16_f32 v13, v16, v13
	ds_read_b128 v[14:17], v47 offset:12672
	ds_read_b128 v[18:21], v47 offset:12688
	s_waitcnt lgkmcnt(1)
; __device__ __forceinline__ unsigned cvtpk(float lo, float hi) { unsigned r; asm volatile("v_cvt_pk_bf16_f32 %0, %1, %2" : "=v"(r) : "v"(lo), "v"(hi)); return r; }
; __device__ __forceinline__ float silu(float z) { return z * __builtin_amdgcn_rcpf(1.0f + __builtin_amdgcn_exp2f(-1.4426950408889634f * z)); }
; template <bool NORM>
; __device__ __forceinline__ void out_rows(const f32x16* o, const float* rli_or_null, char* lds, const float* gain, const float gscale,
;                                          const bf16_t* Z, bf16_t* O, const size_t obase  ) {
;     ...
;   for (int it = 0; it < 8; ++it) { const int row = it * 4 + rsub;
;     f32x4 v0 = *(const f32x4*)(stg + row * STG_LD + c8), v1 = *(const f32x4*)(stg + row * STG_LD + c8 + 4);
;     const size_t off = obase + (size_t)row * 1024 + c8;
;     const u32x4 zv = zq[it];
;     if constexpr (NORM) {
;       float ssq = (v0[0] * v0[0] + v0[1] * v0[1]) + (v0[2] * v0[2] + v0[3] * v0[3]) + (v1[0] * v1[0] + v1[1] * v1[1]) + (v1[2] * v1[2] + v1[3] * v1[3]);
;       ssq += __shfl_xor(ssq, 1); ssq += __shfl_xor(ssq, 2); ssq += __shfl_xor(ssq, 4); ssq += __shfl_xor(ssq, 8);
;       const float rstd = __builtin_amdgcn_rsqf(ssq * (1.0f / 128.0f) + 1e-6f);
;       v0 = v0 * rstd * g0; v1 = v1 * rstd * g1; }
;     v0[0] *= silu(__uint_as_float(zv.x << 16)); v0[1] *= silu(__uint_as_float(zv.x & 0xffff0000u));
;     v0[2] *= silu(__uint_as_float(zv.y << 16)); v0[3] *= silu(__uint_as_float(zv.y & 0xffff0000u));
;     v1[0] *= silu(__uint_as_float(zv.z << 16)); v1[1] *= silu(__uint_as_float(zv.z & 0xffff0000u));
;     v1[2] *= silu(__uint_as_float(zv.w << 16)); v1[3] *= silu(__uint_as_float(zv.w & 0xffff0000u));
;     u32x4 w = {cvtpk(v0[0], v0[1]), cvtpk(v0[2], v0[3]), cvtpk(v1[0], v1[1]), cvtpk(v1[2], v1[3])};
;     __builtin_nontemporal_store(w, (u32x4*)(O + off)); }
	v_pk_mul_f32 v[22:23], v[16:17], v[16:17]
	v_pk_mul_f32 v[24:25], v[14:15], v[14:15]
	s_nop 0
	v_pk_mov_b32 v[26:27], v[24:25], v[22:23] op_sel:[1,0]
	v_mov_b32_e32 v25, v23
	v_pk_add_f32 v[22:23], v[26:27], v[24:25]
	s_waitcnt lgkmcnt(0)
	v_pk_mul_f32 v[24:25], v[20:21], v[20:21]
	v_pk_mul_f32 v[26:27], v[18:19], v[18:19]
	v_mov_b32_e32 v28, v24
	v_mov_b32_e32 v29, v26
	v_mov_b32_e32 v26, v25
	v_pk_add_f32 v[24:25], v[28:29], v[26:27]
	v_add_f32_e32 v0, v22, v23
	v_add_f32_e32 v0, v0, v25
	v_add_f32_e32 v0, v24, v0
	s_nop 1
	v_mov_b32_dpp v22, v0 quad_perm:[1,0,3,2] row_mask:0xf bank_mask:0xf
	s_waitcnt lgkmcnt(0)
	v_add_f32_e32 v0, v0, v22
	s_nop 1
	v_mov_b32_dpp v22, v0 quad_perm:[2,3,0,1] row_mask:0xf bank_mask:0xf
	s_waitcnt lgkmcnt(0)
	v_add_f32_e32 v0, v0, v22
	s_nop 1
	v_mov_b32_dpp v22, v0 row_half_mirror row_mask:0xf bank_mask:0xf
	s_waitcnt lgkmcnt(0)
	v_add_f32_e32 v0, v0, v22
	s_nop 1
	v_mov_b32_dpp v22, v0 row_mirror row_mask:0xf bank_mask:0xf
	s_waitcnt lgkmcnt(0)
	v_add_f32_e32 v0, v0, v22
	v_fmamk_f32 v0, v0, 0x3c000000, v192
	v_rsq_f32_e32 v22, v0
	v_or_b32_e32 v0, 0xa000, v34
	v_lshl_add_u64 v[24:25], v[30:31], 0, v[0:1]
	v_lshlrev_b32_e32 v0, 16, v6
	global_store_dwordx4 v[24:25], v[10:13], off nt
	v_and_b32_e32 v6, 0xffff0000, v6
	s_nop 0
	v_pk_mul_f32 v[10:11], v[14:15], v[22:23] op_sel_hi:[1,0]
	v_pk_mul_f32 v[14:15], v[18:19], v[22:23] op_sel_hi:[1,0]
	v_mul_f32_e32 v18, 0xbfb8aa3b, v0
	v_exp_f32_e32 v18, v18
	v_mul_f32_e32 v19, 0xbfb8aa3b, v6
	v_exp_f32_e32 v19, v19
	v_pk_mul_f32 v[10:11], v[40:41], v[10:11]
	v_add_f32_e32 v18, 1.0, v18
	v_rcp_f32_e32 v18, v18
	v_add_f32_e32 v19, 1.0, v19
	v_rcp_f32_e32 v19, v19
	v_pk_mul_f32 v[12:13], v[16:17], v[22:23] op_sel_hi:[1,0]
	v_mul_f32_e32 v0, v18, v0
	v_mul_f32_e32 v0, v0, v10
	v_lshlrev_b32_e32 v10, 16, v7
	v_and_b32_e32 v7, 0xffff0000, v7
	v_mul_f32_e32 v6, v19, v6
	v_mul_f32_e32 v18, 0xbfb8aa3b, v10
	v_mul_f32_e32 v19, 0xbfb8aa3b, v7
	v_exp_f32_e32 v18, v18
	v_exp_f32_e32 v19, v19
	v_mul_f32_e32 v6, v6, v11
	v_pk_mul_f32 v[16:17], v[20:21], v[22:23] op_sel_hi:[1,0]
	v_add_f32_e32 v11, 1.0, v18
	v_add_f32_e32 v18, 1.0, v19
	v_lshlrev_b32_e32 v19, 16, v8
	v_mul_f32_e32 v20, 0xbfb8aa3b, v19
	v_rcp_f32_e32 v11, v11
	v_exp_f32_e32 v20, v20
	v_pk_mul_f32 v[12:13], v[42:43], v[12:13]
	v_rcp_f32_e32 v18, v18
	v_mul_f32_e32 v10, v11, v10
	v_add_f32_e32 v11, 1.0, v20
	v_and_b32_e32 v8, 0xffff0000, v8
	v_mul_f32_e32 v10, v10, v12
	v_rcp_f32_e32 v11, v11
	v_mul_f32_e32 v12, 0xbfb8aa3b, v8
	v_exp_f32_e32 v12, v12
	v_mul_f32_e32 v7, v18, v7
	v_pk_mul_f32 v[14:15], v[36:37], v[14:15]
	v_mul_f32_e32 v7, v7, v13
	v_mul_f32_e32 v11, v11, v19
	v_lshlrev_b32_e32 v13, 16, v9
	v_and_b32_e32 v9, 0xffff0000, v9
	v_mul_f32_e32 v11, v11, v14
	v_add_f32_e32 v12, 1.0, v12
	v_mul_f32_e32 v14, 0xbfb8aa3b, v13
	v_mul_f32_e32 v18, 0xbfb8aa3b, v9
	v_rcp_f32_e32 v12, v12
	v_exp_f32_e32 v14, v14
	v_exp_f32_e32 v18, v18
	v_pk_mul_f32 v[16:17], v[38:39], v[16:17]
	v_mul_f32_e32 v8, v12, v8
	v_add_f32_e32 v12, 1.0, v14
	v_add_f32_e32 v14, 1.0, v18
	v_rcp_f32_e32 v12, v12
	v_rcp_f32_e32 v14, v14
	v_mul_f32_e32 v8, v8, v15
	v_cvt_pk_bf16_f32 v6, v0, v6
	v_mul_f32_e32 v12, v12, v13
	v_mul_f32_e32 v9, v14, v9
	v_mul_f32_e32 v12, v12, v16
	v_mul_f32_e32 v9, v9, v17
	v_cvt_pk_bf16_f32 v7, v10, v7
	v_cvt_pk_bf16_f32 v8, v11, v8
	v_cvt_pk_bf16_f32 v9, v12, v9
	ds_read_b128 v[10:13], v47 offset:14784
	ds_read_b128 v[14:17], v47 offset:14800
	s_waitcnt lgkmcnt(1)
	v_pk_mul_f32 v[18:19], v[12:13], v[12:13]
	v_pk_mul_f32 v[20:21], v[10:11], v[10:11]
	s_nop 0
	v_pk_mov_b32 v[22:23], v[20:21], v[18:19] op_sel:[1,0]
	v_mov_b32_e32 v21, v19
	v_pk_add_f32 v[18:19], v[22:23], v[20:21]
	s_waitcnt lgkmcnt(0)
	v_pk_mul_f32 v[20:21], v[16:17], v[16:17]
	v_pk_mul_f32 v[22:23], v[14:15], v[14:15]
	v_mov_b32_e32 v24, v20
	v_mov_b32_e32 v25, v22
	v_mov_b32_e32 v22, v21
	v_pk_add_f32 v[20:21], v[24:25], v[22:23]
	v_add_f32_e32 v0, v18, v19
	v_add_f32_e32 v0, v0, v21
	v_add_f32_e32 v0, v20, v0
	s_nop 1
	v_mov_b32_dpp v18, v0 quad_perm:[1,0,3,2] row_mask:0xf bank_mask:0xf
	s_waitcnt lgkmcnt(0)
	v_add_f32_e32 v0, v0, v18
	s_nop 1
	v_mov_b32_dpp v18, v0 quad_perm:[2,3,0,1] row_mask:0xf bank_mask:0xf
	s_waitcnt lgkmcnt(0)
	v_add_f32_e32 v0, v0, v18
	s_nop 1
	v_mov_b32_dpp v18, v0 row_half_mirror row_mask:0xf bank_mask:0xf
	s_waitcnt lgkmcnt(0)
	v_add_f32_e32 v0, v0, v18
	s_nop 1
	v_mov_b32_dpp v18, v0 row_mirror row_mask:0xf bank_mask:0xf
	s_waitcnt lgkmcnt(0)
	v_add_f32_e32 v0, v0, v18
	v_fmamk_f32 v0, v0, 0x3c000000, v192
	v_rsq_f32_e32 v18, v0
	v_or_b32_e32 v0, 0xc000, v34
	v_lshl_add_u64 v[20:21], v[30:31], 0, v[0:1]
	v_lshlrev_b32_e32 v0, 16, v2
	global_store_dwordx4 v[20:21], v[6:9], off nt
	v_and_b32_e32 v2, 0xffff0000, v2
	s_nop 0
	v_pk_mul_f32 v[6:7], v[10:11], v[18:19] op_sel_hi:[1,0]
	v_pk_mul_f32 v[10:11], v[14:15], v[18:19] op_sel_hi:[1,0]
	v_mul_f32_e32 v14, 0xbfb8aa3b, v0
	v_exp_f32_e32 v14, v14
	v_mul_f32_e32 v15, 0xbfb8aa3b, v2
	v_exp_f32_e32 v15, v15
	v_pk_mul_f32 v[6:7], v[40:41], v[6:7]
	v_add_f32_e32 v14, 1.0, v14
	v_rcp_f32_e32 v14, v14
	v_add_f32_e32 v15, 1.0, v15
	v_rcp_f32_e32 v15, v15
	v_pk_mul_f32 v[8:9], v[12:13], v[18:19] op_sel_hi:[1,0]
	v_mul_f32_e32 v0, v14, v0
	v_mul_f32_e32 v0, v0, v6
	v_lshlrev_b32_e32 v6, 16, v3
	v_and_b32_e32 v3, 0xffff0000, v3
	v_mul_f32_e32 v2, v15, v2
	v_mul_f32_e32 v14, 0xbfb8aa3b, v6
	v_mul_f32_e32 v15, 0xbfb8aa3b, v3
	v_exp_f32_e32 v14, v14
	v_exp_f32_e32 v15, v15
	v_mul_f32_e32 v2, v2, v7
	v_pk_mul_f32 v[12:13], v[16:17], v[18:19] op_sel_hi:[1,0]
	v_add_f32_e32 v7, 1.0, v14
	v_add_f32_e32 v14, 1.0, v15
	v_lshlrev_b32_e32 v15, 16, v4
	v_mul_f32_e32 v16, 0xbfb8aa3b, v15
	v_rcp_f32_e32 v7, v7
	v_exp_f32_e32 v16, v16
	v_pk_mul_f32 v[8:9], v[42:43], v[8:9]
	v_rcp_f32_e32 v14, v14
	v_mul_f32_e32 v6, v7, v6
	v_add_f32_e32 v7, 1.0, v16
	v_and_b32_e32 v4, 0xffff0000, v4
	v_mul_f32_e32 v6, v6, v8
	v_rcp_f32_e32 v7, v7
	v_mul_f32_e32 v8, 0xbfb8aa3b, v4
	v_exp_f32_e32 v8, v8
	v_mul_f32_e32 v3, v14, v3
	v_pk_mul_f32 v[10:11], v[36:37], v[10:11]
	v_mul_f32_e32 v3, v3, v9
	v_mul_f32_e32 v7, v7, v15
	v_lshlrev_b32_e32 v9, 16, v5
	v_and_b32_e32 v5, 0xffff0000, v5
	v_mul_f32_e32 v7, v7, v10
	v_add_f32_e32 v8, 1.0, v8
	v_mul_f32_e32 v10, 0xbfb8aa3b, v9
	v_mul_f32_e32 v14, 0xbfb8aa3b, v5
	v_rcp_f32_e32 v8, v8
	v_exp_f32_e32 v10, v10
	v_exp_f32_e32 v14, v14
	v_pk_mul_f32 v[12:13], v[38:39], v[12:13]
	v_mul_f32_e32 v4, v8, v4
	v_add_f32_e32 v8, 1.0, v10
	v_add_f32_e32 v10, 1.0, v14
	v_rcp_f32_e32 v10, v10
	v_rcp_f32_e32 v8, v8
	v_mul_f32_e32 v4, v4, v11
	v_cvt_pk_bf16_f32 v2, v0, v2
	v_mul_f32_e32 v5, v10, v5
	v_or_b32_e32 v0, 0xe000, v34
	v_mul_f32_e32 v8, v8, v9
	v_mul_f32_e32 v5, v5, v13
	v_cvt_pk_bf16_f32 v3, v6, v3
	v_cvt_pk_bf16_f32 v4, v7, v4
	v_lshl_add_u64 v[6:7], v[30:31], 0, v[0:1]
	v_mul_f32_e32 v8, v8, v12
	v_cvt_pk_bf16_f32 v5, v8, v5
	global_store_dwordx4 v[6:7], v[2:5], off nt
	s_barrier
	s_cbranch_scc1 .LBB0_207
